# mini GEMM tiles: permuted lane order so each 16-lane group loads 4 rows x 64 contiguous bytes, ds_bpermute back to MFMA order, 8 k-steps in flight; plus v010 edits and P1 store coalescing
# speedup vs baseline: 1.0174x; 1.0174x over previous
; DEVI f32x4 mfma16(bf16x8 a, bf16x8 b, f32x4 c) { return __builtin_amdgcn_mfma_f32_16x16x32_bf16(a, b, c, 0, 0, 0); }
; DEVI void mini_kloop(const bf16_t* __restrict__ arow, const bf16_t* __restrict__ b0, const bf16_t* __restrict__ b1, const int K, f32x4 (&acc)[2]) {
; #pragma unroll 8
;     for (int k0 = 0; k0 < K; k0 += 32) {
;         const bf16x8 af = *(const bf16x8*)(arow + k0), w0 = *(const bf16x8*)(b0 + k0), w1 = *(const bf16x8*)(b1 + k0);
;         acc[0] = mfma16(w0, af, acc[0]); acc[1] = mfma16(w1, af, acc[1]);
;     }
; }
; DEVI void mini_mix_tile(const Params& p, const int t) {
;     int tid = threadIdx.x; asm volatile("" : "+v"(tid));
;     const int lane = tid & 63, w = tid >> 6, l15 = lane & 15, g = lane >> 4;
;     const int tok = NTP + 64 * (t >> 4) + 16 * (w & 3) + l15, colw = 64 * (t & 15) + 32 * (w >> 2);
;     const bf16_t* OA = (const bf16_t*)(p.ws + W_OAB); const bf16_t* OB = OA + (size_t)NTOK * 512;
;     const bf16_t* WAT = (const bf16_t*)(p.ws + W_WABT); const bf16_t* WBT = WAT + 1024 * 512;
;     f32x4 aa[2] = {(f32x4){0.f, 0.f, 0.f, 0.f}, (f32x4){0.f, 0.f, 0.f, 0.f}}, ab[2] = {(f32x4){0.f, 0.f, 0.f, 0.f}, (f32x4){0.f, 0.f, 0.f, 0.f}};
;     mini_kloop(OA + (size_t)tok * 512 + 8 * g, WAT + (size_t)(colw + l15) * 512 + 8 * g, WAT + (size_t)(colw + 16 + l15) * 512 + 8 * g, 512, aa);
;     mini_kloop(OB + (size_t)tok * 512 + 8 * g, WBT + (size_t)(colw + l15) * 512 + 8 * g, WBT + (size_t)(colw + 16 + l15) * 512 + 8 * g, 512, ab);
.LBB0_995:
	v_mov_b32_e32 v8, 0
	v_mov_b32_e32 v9, 0
	v_mov_b32_e32 v10, 0
	v_mov_b32_e32 v11, 0
	v_mov_b32_e32 v12, 0
	v_mov_b32_e32 v13, 0
	v_mov_b32_e32 v14, 0
	v_mov_b32_e32 v15, 0
	v_lshl_add_u64 v[28:29], v[18:19], 0, v[16:17]
	v_lshl_add_u64 v[30:31], v[20:21], 0, v[16:17]
	v_lshl_add_u64 v[32:33], v[22:23], 0, v[16:17]
	v_add_co_u32_e32 v34, vcc, 0x1af48000, v28
	s_nop 1
	v_addc_co_u32_e32 v35, vcc, 0, v29, vcc
	v_add_co_u32_e32 v28, vcc, 0x18e48000, v28
	s_nop 1
	v_addc_co_u32_e32 v29, vcc, 0, v29, vcc
	v_add_co_u32_e32 v36, vcc, 0x5080000, v30
	s_nop 1
	v_addc_co_u32_e32 v37, vcc, 0, v31, vcc
	v_add_co_u32_e32 v30, vcc, 0x4f80000, v30
	s_nop 1
	v_addc_co_u32_e32 v31, vcc, 0, v31, vcc
	v_add_co_u32_e32 v38, vcc, 0x5080000, v32
	s_nop 1
	v_addc_co_u32_e32 v39, vcc, 0, v33, vcc
	v_add_co_u32_e32 v32, vcc, 0x4f80000, v32
	s_nop 1
	v_addc_co_u32_e32 v33, vcc, 0, v33, vcc
	v_and_b32_e32 v40, 63, v203
	v_and_b32_e32 v41, 3, v40
	v_lshrrev_b32_e32 v42, 4, v40
	v_bfe_u32 v43, v40, 2, 2
	v_lshl_add_u32 v44, v42, 2, v43
	v_lshl_add_u32 v44, v41, 4, v44
	v_lshlrev_b32_e32 v44, 2, v44
	v_lshlrev_b32_e32 v45, 4, v43
	v_lshl_add_u32 v45, v41, 2, v45
	v_add_u32_e32 v45, v45, v42
	v_lshlrev_b32_e32 v45, 2, v45
	ds_bpermute_b32 v28, v44, v28
	ds_bpermute_b32 v29, v44, v29
	ds_bpermute_b32 v30, v44, v30
	ds_bpermute_b32 v31, v44, v31
	ds_bpermute_b32 v32, v44, v32
	ds_bpermute_b32 v33, v44, v33
	ds_bpermute_b32 v34, v44, v34
	ds_bpermute_b32 v35, v44, v35
	ds_bpermute_b32 v36, v44, v36
	ds_bpermute_b32 v37, v44, v37
	ds_bpermute_b32 v38, v44, v38
	ds_bpermute_b32 v39, v44, v39
	s_waitcnt lgkmcnt(0)
	global_load_dwordx4 v[64:67], v[28:29], off
	global_load_dwordx4 v[68:71], v[30:31], off
	global_load_dwordx4 v[72:75], v[32:33], off
	global_load_dwordx4 v[76:79], v[28:29], off offset:64
	global_load_dwordx4 v[80:83], v[30:31], off offset:64
	global_load_dwordx4 v[84:87], v[32:33], off offset:64
	global_load_dwordx4 v[88:91], v[28:29], off offset:128
	global_load_dwordx4 v[92:95], v[30:31], off offset:128
	global_load_dwordx4 v[96:99], v[32:33], off offset:128
	global_load_dwordx4 v[100:103], v[28:29], off offset:192
	global_load_dwordx4 v[104:107], v[30:31], off offset:192
	global_load_dwordx4 v[108:111], v[32:33], off offset:192
	global_load_dwordx4 v[112:115], v[28:29], off offset:256
	global_load_dwordx4 v[116:119], v[30:31], off offset:256
	global_load_dwordx4 v[120:123], v[32:33], off offset:256
	global_load_dwordx4 v[124:127], v[28:29], off offset:320
	global_load_dwordx4 v[128:131], v[30:31], off offset:320
	global_load_dwordx4 v[132:135], v[32:33], off offset:320
	global_load_dwordx4 v[136:139], v[28:29], off offset:384
	global_load_dwordx4 v[140:143], v[30:31], off offset:384
	global_load_dwordx4 v[144:147], v[32:33], off offset:384
	global_load_dwordx4 v[148:151], v[28:29], off offset:448
	global_load_dwordx4 v[152:155], v[30:31], off offset:448
	global_load_dwordx4 v[156:159], v[32:33], off offset:448
	s_waitcnt vmcnt(21)
	ds_bpermute_b32 v160, v45, v64
	ds_bpermute_b32 v161, v45, v65
	ds_bpermute_b32 v162, v45, v66
	ds_bpermute_b32 v163, v45, v67
	ds_bpermute_b32 v164, v45, v68
	ds_bpermute_b32 v165, v45, v69
	ds_bpermute_b32 v166, v45, v70
	ds_bpermute_b32 v167, v45, v71
	ds_bpermute_b32 v168, v45, v72
	ds_bpermute_b32 v169, v45, v73
	ds_bpermute_b32 v170, v45, v74
	ds_bpermute_b32 v171, v45, v75
	s_waitcnt vmcnt(18)
	s_waitcnt lgkmcnt(3)
	ds_bpermute_b32 v172, v45, v76
	ds_bpermute_b32 v173, v45, v77
	ds_bpermute_b32 v174, v45, v78
	ds_bpermute_b32 v175, v45, v79
	ds_bpermute_b32 v176, v45, v80
	ds_bpermute_b32 v177, v45, v81
	ds_bpermute_b32 v178, v45, v82
	ds_bpermute_b32 v179, v45, v83
	ds_bpermute_b32 v180, v45, v84
	ds_bpermute_b32 v181, v45, v85
	ds_bpermute_b32 v182, v45, v86
	ds_bpermute_b32 v183, v45, v87
	s_waitcnt lgkmcnt(12)
	v_mfma_f32_16x16x32_bf16 v[4:7], v[164:167], v[160:163], v[4:7]
	v_mfma_f32_16x16x32_bf16 v[0:3], v[168:171], v[160:163], v[0:3]
	global_load_dwordx4 v[64:67], v[28:29], off offset:512
	global_load_dwordx4 v[68:71], v[30:31], off offset:512
	global_load_dwordx4 v[72:75], v[32:33], off offset:512
	s_waitcnt vmcnt(18)
	s_waitcnt lgkmcnt(3)
	ds_bpermute_b32 v160, v45, v88
	ds_bpermute_b32 v161, v45, v89
	ds_bpermute_b32 v162, v45, v90
	ds_bpermute_b32 v163, v45, v91
	ds_bpermute_b32 v164, v45, v92
	ds_bpermute_b32 v165, v45, v93
	ds_bpermute_b32 v166, v45, v94
	ds_bpermute_b32 v167, v45, v95
	ds_bpermute_b32 v168, v45, v96
	ds_bpermute_b32 v169, v45, v97
	ds_bpermute_b32 v170, v45, v98
	ds_bpermute_b32 v171, v45, v99
	s_waitcnt lgkmcnt(12)
	v_mfma_f32_16x16x32_bf16 v[4:7], v[176:179], v[172:175], v[4:7]
	v_mfma_f32_16x16x32_bf16 v[0:3], v[180:183], v[172:175], v[0:3]
	global_load_dwordx4 v[76:79], v[28:29], off offset:576
	global_load_dwordx4 v[80:83], v[30:31], off offset:576
	global_load_dwordx4 v[84:87], v[32:33], off offset:576
	s_waitcnt vmcnt(18)
	s_waitcnt lgkmcnt(3)
	ds_bpermute_b32 v172, v45, v100
	ds_bpermute_b32 v173, v45, v101
	ds_bpermute_b32 v174, v45, v102
	ds_bpermute_b32 v175, v45, v103
	ds_bpermute_b32 v176, v45, v104
	ds_bpermute_b32 v177, v45, v105
	ds_bpermute_b32 v178, v45, v106
	ds_bpermute_b32 v179, v45, v107
	ds_bpermute_b32 v180, v45, v108
	ds_bpermute_b32 v181, v45, v109
	ds_bpermute_b32 v182, v45, v110
	ds_bpermute_b32 v183, v45, v111
	s_waitcnt lgkmcnt(12)
	v_mfma_f32_16x16x32_bf16 v[4:7], v[164:167], v[160:163], v[4:7]
	v_mfma_f32_16x16x32_bf16 v[0:3], v[168:171], v[160:163], v[0:3]
	global_load_dwordx4 v[88:91], v[28:29], off offset:640
	global_load_dwordx4 v[92:95], v[30:31], off offset:640
	global_load_dwordx4 v[96:99], v[32:33], off offset:640
	s_waitcnt vmcnt(18)
; DEVI f32x4 mfma16(bf16x8 a, bf16x8 b, f32x4 c) { return __builtin_amdgcn_mfma_f32_16x16x32_bf16(a, b, c, 0, 0, 0); }
; DEVI void mini_kloop(const bf16_t* __restrict__ arow, const bf16_t* __restrict__ b0, const bf16_t* __restrict__ b1, const int K, f32x4 (&acc)[2]) {
; #pragma unroll 8
;     for (int k0 = 0; k0 < K; k0 += 32) {
;         const bf16x8 af = *(const bf16x8*)(arow + k0), w0 = *(const bf16x8*)(b0 + k0), w1 = *(const bf16x8*)(b1 + k0);
;         acc[0] = mfma16(w0, af, acc[0]); acc[1] = mfma16(w1, af, acc[1]);
;     }
; }
; DEVI void mini_mix_tile(const Params& p, const int t) {
;     ...
;     mini_kloop(OA + (size_t)tok * 512 + 8 * g, WAT + (size_t)(colw + l15) * 512 + 8 * g, WAT + (size_t)(colw + 16 + l15) * 512 + 8 * g, 512, aa);
;     mini_kloop(OB + (size_t)tok * 512 + 8 * g, WBT + (size_t)(colw + l15) * 512 + 8 * g, WBT + (size_t)(colw + 16 + l15) * 512 + 8 * g, 512, ab);
	s_waitcnt lgkmcnt(3)
	ds_bpermute_b32 v160, v45, v112
	ds_bpermute_b32 v161, v45, v113
	ds_bpermute_b32 v162, v45, v114
	ds_bpermute_b32 v163, v45, v115
	ds_bpermute_b32 v164, v45, v116
	ds_bpermute_b32 v165, v45, v117
	ds_bpermute_b32 v166, v45, v118
	ds_bpermute_b32 v167, v45, v119
	ds_bpermute_b32 v168, v45, v120
	ds_bpermute_b32 v169, v45, v121
	ds_bpermute_b32 v170, v45, v122
	ds_bpermute_b32 v171, v45, v123
	s_waitcnt lgkmcnt(12)
	v_mfma_f32_16x16x32_bf16 v[4:7], v[176:179], v[172:175], v[4:7]
	v_mfma_f32_16x16x32_bf16 v[0:3], v[180:183], v[172:175], v[0:3]
	global_load_dwordx4 v[100:103], v[28:29], off offset:704
	global_load_dwordx4 v[104:107], v[30:31], off offset:704
	global_load_dwordx4 v[108:111], v[32:33], off offset:704
	s_waitcnt vmcnt(18)
	s_waitcnt lgkmcnt(3)
	ds_bpermute_b32 v172, v45, v124
	ds_bpermute_b32 v173, v45, v125
	ds_bpermute_b32 v174, v45, v126
	ds_bpermute_b32 v175, v45, v127
	ds_bpermute_b32 v176, v45, v128
	ds_bpermute_b32 v177, v45, v129
	ds_bpermute_b32 v178, v45, v130
	ds_bpermute_b32 v179, v45, v131
	ds_bpermute_b32 v180, v45, v132
	ds_bpermute_b32 v181, v45, v133
	ds_bpermute_b32 v182, v45, v134
	ds_bpermute_b32 v183, v45, v135
	s_waitcnt lgkmcnt(12)
	v_mfma_f32_16x16x32_bf16 v[4:7], v[164:167], v[160:163], v[4:7]
	v_mfma_f32_16x16x32_bf16 v[0:3], v[168:171], v[160:163], v[0:3]
	global_load_dwordx4 v[112:115], v[28:29], off offset:768
	global_load_dwordx4 v[116:119], v[30:31], off offset:768
	global_load_dwordx4 v[120:123], v[32:33], off offset:768
	s_waitcnt vmcnt(18)
	s_waitcnt lgkmcnt(3)
	ds_bpermute_b32 v160, v45, v136
	ds_bpermute_b32 v161, v45, v137
	ds_bpermute_b32 v162, v45, v138
	ds_bpermute_b32 v163, v45, v139
	ds_bpermute_b32 v164, v45, v140
	ds_bpermute_b32 v165, v45, v141
	ds_bpermute_b32 v166, v45, v142
	ds_bpermute_b32 v167, v45, v143
	ds_bpermute_b32 v168, v45, v144
	ds_bpermute_b32 v169, v45, v145
	ds_bpermute_b32 v170, v45, v146
	ds_bpermute_b32 v171, v45, v147
	s_waitcnt lgkmcnt(12)
	v_mfma_f32_16x16x32_bf16 v[4:7], v[176:179], v[172:175], v[4:7]
	v_mfma_f32_16x16x32_bf16 v[0:3], v[180:183], v[172:175], v[0:3]
	global_load_dwordx4 v[124:127], v[28:29], off offset:832
	global_load_dwordx4 v[128:131], v[30:31], off offset:832
	global_load_dwordx4 v[132:135], v[32:33], off offset:832
	s_waitcnt vmcnt(18)
	s_waitcnt lgkmcnt(3)
	ds_bpermute_b32 v172, v45, v148
	ds_bpermute_b32 v173, v45, v149
	ds_bpermute_b32 v174, v45, v150
	ds_bpermute_b32 v175, v45, v151
	ds_bpermute_b32 v176, v45, v152
	ds_bpermute_b32 v177, v45, v153
	ds_bpermute_b32 v178, v45, v154
	ds_bpermute_b32 v179, v45, v155
	ds_bpermute_b32 v180, v45, v156
	ds_bpermute_b32 v181, v45, v157
	ds_bpermute_b32 v182, v45, v158
	ds_bpermute_b32 v183, v45, v159
	s_waitcnt lgkmcnt(12)
	v_mfma_f32_16x16x32_bf16 v[4:7], v[164:167], v[160:163], v[4:7]
	v_mfma_f32_16x16x32_bf16 v[0:3], v[168:171], v[160:163], v[0:3]
	global_load_dwordx4 v[136:139], v[28:29], off offset:896
	global_load_dwordx4 v[140:143], v[30:31], off offset:896
	global_load_dwordx4 v[144:147], v[32:33], off offset:896
	s_waitcnt vmcnt(18)
	s_waitcnt lgkmcnt(3)
	ds_bpermute_b32 v160, v45, v64
	ds_bpermute_b32 v161, v45, v65
	ds_bpermute_b32 v162, v45, v66
	ds_bpermute_b32 v163, v45, v67
	ds_bpermute_b32 v164, v45, v68
	ds_bpermute_b32 v165, v45, v69
	ds_bpermute_b32 v166, v45, v70
	ds_bpermute_b32 v167, v45, v71
	ds_bpermute_b32 v168, v45, v72
	ds_bpermute_b32 v169, v45, v73
	ds_bpermute_b32 v170, v45, v74
	ds_bpermute_b32 v171, v45, v75
	s_waitcnt lgkmcnt(12)
	v_mfma_f32_16x16x32_bf16 v[4:7], v[176:179], v[172:175], v[4:7]
	v_mfma_f32_16x16x32_bf16 v[0:3], v[180:183], v[172:175], v[0:3]
	global_load_dwordx4 v[148:151], v[28:29], off offset:960
	global_load_dwordx4 v[152:155], v[30:31], off offset:960
	global_load_dwordx4 v[156:159], v[32:33], off offset:960
	s_waitcnt vmcnt(18)
	s_waitcnt lgkmcnt(3)
	ds_bpermute_b32 v172, v45, v76
	ds_bpermute_b32 v173, v45, v77
	ds_bpermute_b32 v174, v45, v78
	ds_bpermute_b32 v175, v45, v79
	ds_bpermute_b32 v176, v45, v80
	ds_bpermute_b32 v177, v45, v81
	ds_bpermute_b32 v178, v45, v82
	ds_bpermute_b32 v179, v45, v83
	ds_bpermute_b32 v180, v45, v84
	ds_bpermute_b32 v181, v45, v85
	ds_bpermute_b32 v182, v45, v86
	ds_bpermute_b32 v183, v45, v87
	s_waitcnt lgkmcnt(12)
	v_mfma_f32_16x16x32_bf16 v[4:7], v[164:167], v[160:163], v[4:7]
	v_mfma_f32_16x16x32_bf16 v[0:3], v[168:171], v[160:163], v[0:3]
	global_load_dwordx4 v[64:67], v[34:35], off
	global_load_dwordx4 v[68:71], v[36:37], off
	global_load_dwordx4 v[72:75], v[38:39], off
	s_waitcnt vmcnt(18)
	s_waitcnt lgkmcnt(3)
	ds_bpermute_b32 v160, v45, v88
	ds_bpermute_b32 v161, v45, v89
	ds_bpermute_b32 v162, v45, v90
	ds_bpermute_b32 v163, v45, v91
	ds_bpermute_b32 v164, v45, v92
	ds_bpermute_b32 v165, v45, v93
	ds_bpermute_b32 v166, v45, v94
	ds_bpermute_b32 v167, v45, v95
	ds_bpermute_b32 v168, v45, v96
	ds_bpermute_b32 v169, v45, v97
	ds_bpermute_b32 v170, v45, v98
	ds_bpermute_b32 v171, v45, v99
	s_waitcnt lgkmcnt(12)
	v_mfma_f32_16x16x32_bf16 v[4:7], v[176:179], v[172:175], v[4:7]
	v_mfma_f32_16x16x32_bf16 v[0:3], v[180:183], v[172:175], v[0:3]
	global_load_dwordx4 v[76:79], v[34:35], off offset:64
	global_load_dwordx4 v[80:83], v[36:37], off offset:64
	global_load_dwordx4 v[84:87], v[38:39], off offset:64
	s_waitcnt vmcnt(18)
	s_waitcnt lgkmcnt(3)
	ds_bpermute_b32 v172, v45, v100
	ds_bpermute_b32 v173, v45, v101
	ds_bpermute_b32 v174, v45, v102
	ds_bpermute_b32 v175, v45, v103
	ds_bpermute_b32 v176, v45, v104
	ds_bpermute_b32 v177, v45, v105
	ds_bpermute_b32 v178, v45, v106
	ds_bpermute_b32 v179, v45, v107
	ds_bpermute_b32 v180, v45, v108
	ds_bpermute_b32 v181, v45, v109
	ds_bpermute_b32 v182, v45, v110
	ds_bpermute_b32 v183, v45, v111
	s_waitcnt lgkmcnt(12)
; DEVI f32x4 mfma16(bf16x8 a, bf16x8 b, f32x4 c) { return __builtin_amdgcn_mfma_f32_16x16x32_bf16(a, b, c, 0, 0, 0); }
; DEVI void mini_kloop(const bf16_t* __restrict__ arow, const bf16_t* __restrict__ b0, const bf16_t* __restrict__ b1, const int K, f32x4 (&acc)[2]) {
; #pragma unroll 8
;     for (int k0 = 0; k0 < K; k0 += 32) {
;         const bf16x8 af = *(const bf16x8*)(arow + k0), w0 = *(const bf16x8*)(b0 + k0), w1 = *(const bf16x8*)(b1 + k0);
;         acc[0] = mfma16(w0, af, acc[0]); acc[1] = mfma16(w1, af, acc[1]);
;     }
; }
; DEVI void mini_mix_tile(const Params& p, const int t) {
;     ...
;     mini_kloop(OA + (size_t)tok * 512 + 8 * g, WAT + (size_t)(colw + l15) * 512 + 8 * g, WAT + (size_t)(colw + 16 + l15) * 512 + 8 * g, 512, aa);
;     mini_kloop(OB + (size_t)tok * 512 + 8 * g, WBT + (size_t)(colw + l15) * 512 + 8 * g, WBT + (size_t)(colw + 16 + l15) * 512 + 8 * g, 512, ab);
	v_mfma_f32_16x16x32_bf16 v[4:7], v[164:167], v[160:163], v[4:7]
	v_mfma_f32_16x16x32_bf16 v[0:3], v[168:171], v[160:163], v[0:3]
	global_load_dwordx4 v[88:91], v[34:35], off offset:128
	global_load_dwordx4 v[92:95], v[36:37], off offset:128
	global_load_dwordx4 v[96:99], v[38:39], off offset:128
	s_waitcnt vmcnt(18)
	s_waitcnt lgkmcnt(3)
	ds_bpermute_b32 v160, v45, v112
	ds_bpermute_b32 v161, v45, v113
	ds_bpermute_b32 v162, v45, v114
	ds_bpermute_b32 v163, v45, v115
	ds_bpermute_b32 v164, v45, v116
	ds_bpermute_b32 v165, v45, v117
	ds_bpermute_b32 v166, v45, v118
	ds_bpermute_b32 v167, v45, v119
	ds_bpermute_b32 v168, v45, v120
	ds_bpermute_b32 v169, v45, v121
	ds_bpermute_b32 v170, v45, v122
	ds_bpermute_b32 v171, v45, v123
	s_waitcnt lgkmcnt(12)
	v_mfma_f32_16x16x32_bf16 v[4:7], v[176:179], v[172:175], v[4:7]
	v_mfma_f32_16x16x32_bf16 v[0:3], v[180:183], v[172:175], v[0:3]
	global_load_dwordx4 v[100:103], v[34:35], off offset:192
	global_load_dwordx4 v[104:107], v[36:37], off offset:192
	global_load_dwordx4 v[108:111], v[38:39], off offset:192
	s_waitcnt vmcnt(18)
	s_waitcnt lgkmcnt(3)
	ds_bpermute_b32 v172, v45, v124
	ds_bpermute_b32 v173, v45, v125
	ds_bpermute_b32 v174, v45, v126
	ds_bpermute_b32 v175, v45, v127
	ds_bpermute_b32 v176, v45, v128
	ds_bpermute_b32 v177, v45, v129
	ds_bpermute_b32 v178, v45, v130
	ds_bpermute_b32 v179, v45, v131
	ds_bpermute_b32 v180, v45, v132
	ds_bpermute_b32 v181, v45, v133
	ds_bpermute_b32 v182, v45, v134
	ds_bpermute_b32 v183, v45, v135
	s_waitcnt lgkmcnt(12)
	v_mfma_f32_16x16x32_bf16 v[4:7], v[164:167], v[160:163], v[4:7]
	v_mfma_f32_16x16x32_bf16 v[0:3], v[168:171], v[160:163], v[0:3]
	global_load_dwordx4 v[112:115], v[34:35], off offset:256
	global_load_dwordx4 v[116:119], v[36:37], off offset:256
	global_load_dwordx4 v[120:123], v[38:39], off offset:256
	s_waitcnt vmcnt(18)
	s_waitcnt lgkmcnt(3)
	ds_bpermute_b32 v160, v45, v136
	ds_bpermute_b32 v161, v45, v137
	ds_bpermute_b32 v162, v45, v138
	ds_bpermute_b32 v163, v45, v139
	ds_bpermute_b32 v164, v45, v140
	ds_bpermute_b32 v165, v45, v141
	ds_bpermute_b32 v166, v45, v142
	ds_bpermute_b32 v167, v45, v143
	ds_bpermute_b32 v168, v45, v144
	ds_bpermute_b32 v169, v45, v145
	ds_bpermute_b32 v170, v45, v146
	ds_bpermute_b32 v171, v45, v147
	s_waitcnt lgkmcnt(12)
	v_mfma_f32_16x16x32_bf16 v[4:7], v[176:179], v[172:175], v[4:7]
	v_mfma_f32_16x16x32_bf16 v[0:3], v[180:183], v[172:175], v[0:3]
	global_load_dwordx4 v[124:127], v[34:35], off offset:320
	global_load_dwordx4 v[128:131], v[36:37], off offset:320
	global_load_dwordx4 v[132:135], v[38:39], off offset:320
	s_waitcnt vmcnt(18)
	s_waitcnt lgkmcnt(3)
	ds_bpermute_b32 v172, v45, v148
	ds_bpermute_b32 v173, v45, v149
	ds_bpermute_b32 v174, v45, v150
	ds_bpermute_b32 v175, v45, v151
	ds_bpermute_b32 v176, v45, v152
	ds_bpermute_b32 v177, v45, v153
	ds_bpermute_b32 v178, v45, v154
	ds_bpermute_b32 v179, v45, v155
	ds_bpermute_b32 v180, v45, v156
	ds_bpermute_b32 v181, v45, v157
	ds_bpermute_b32 v182, v45, v158
	ds_bpermute_b32 v183, v45, v159
	s_waitcnt lgkmcnt(12)
	v_mfma_f32_16x16x32_bf16 v[4:7], v[164:167], v[160:163], v[4:7]
	v_mfma_f32_16x16x32_bf16 v[0:3], v[168:171], v[160:163], v[0:3]
	global_load_dwordx4 v[136:139], v[34:35], off offset:384
	global_load_dwordx4 v[140:143], v[36:37], off offset:384
	global_load_dwordx4 v[144:147], v[38:39], off offset:384
	s_waitcnt vmcnt(18)
	s_waitcnt lgkmcnt(3)
	ds_bpermute_b32 v160, v45, v64
	ds_bpermute_b32 v161, v45, v65
	ds_bpermute_b32 v162, v45, v66
	ds_bpermute_b32 v163, v45, v67
	ds_bpermute_b32 v164, v45, v68
	ds_bpermute_b32 v165, v45, v69
	ds_bpermute_b32 v166, v45, v70
	ds_bpermute_b32 v167, v45, v71
	ds_bpermute_b32 v168, v45, v72
	ds_bpermute_b32 v169, v45, v73
	ds_bpermute_b32 v170, v45, v74
	ds_bpermute_b32 v171, v45, v75
	s_waitcnt lgkmcnt(12)
	v_mfma_f32_16x16x32_bf16 v[4:7], v[176:179], v[172:175], v[4:7]
	v_mfma_f32_16x16x32_bf16 v[0:3], v[180:183], v[172:175], v[0:3]
	global_load_dwordx4 v[148:151], v[34:35], off offset:448
	global_load_dwordx4 v[152:155], v[36:37], off offset:448
	global_load_dwordx4 v[156:159], v[38:39], off offset:448
	s_waitcnt vmcnt(18)
	s_waitcnt lgkmcnt(3)
	ds_bpermute_b32 v172, v45, v76
	ds_bpermute_b32 v173, v45, v77
	ds_bpermute_b32 v174, v45, v78
	ds_bpermute_b32 v175, v45, v79
	ds_bpermute_b32 v176, v45, v80
	ds_bpermute_b32 v177, v45, v81
	ds_bpermute_b32 v178, v45, v82
	ds_bpermute_b32 v179, v45, v83
	ds_bpermute_b32 v180, v45, v84
	ds_bpermute_b32 v181, v45, v85
	ds_bpermute_b32 v182, v45, v86
	ds_bpermute_b32 v183, v45, v87
	s_waitcnt lgkmcnt(12)
	v_mfma_f32_16x16x32_bf16 v[12:15], v[164:167], v[160:163], v[12:15]
	v_mfma_f32_16x16x32_bf16 v[8:11], v[168:171], v[160:163], v[8:11]
	global_load_dwordx4 v[64:67], v[34:35], off offset:512
	global_load_dwordx4 v[68:71], v[36:37], off offset:512
	global_load_dwordx4 v[72:75], v[38:39], off offset:512
	s_waitcnt vmcnt(18)
	s_waitcnt lgkmcnt(3)
	ds_bpermute_b32 v160, v45, v88
	ds_bpermute_b32 v161, v45, v89
	ds_bpermute_b32 v162, v45, v90
	ds_bpermute_b32 v163, v45, v91
	ds_bpermute_b32 v164, v45, v92
	ds_bpermute_b32 v165, v45, v93
	ds_bpermute_b32 v166, v45, v94
	ds_bpermute_b32 v167, v45, v95
	ds_bpermute_b32 v168, v45, v96
	ds_bpermute_b32 v169, v45, v97
	ds_bpermute_b32 v170, v45, v98
	ds_bpermute_b32 v171, v45, v99
	s_waitcnt lgkmcnt(12)
	v_mfma_f32_16x16x32_bf16 v[12:15], v[176:179], v[172:175], v[12:15]
	v_mfma_f32_16x16x32_bf16 v[8:11], v[180:183], v[172:175], v[8:11]
	global_load_dwordx4 v[76:79], v[34:35], off offset:576
	global_load_dwordx4 v[80:83], v[36:37], off offset:576
	global_load_dwordx4 v[84:87], v[38:39], off offset:576
	s_waitcnt vmcnt(18)
; DEVI f32x4 mfma16(bf16x8 a, bf16x8 b, f32x4 c) { return __builtin_amdgcn_mfma_f32_16x16x32_bf16(a, b, c, 0, 0, 0); }
; DEVI void mini_kloop(const bf16_t* __restrict__ arow, const bf16_t* __restrict__ b0, const bf16_t* __restrict__ b1, const int K, f32x4 (&acc)[2]) {
; #pragma unroll 8
;     for (int k0 = 0; k0 < K; k0 += 32) {
;         const bf16x8 af = *(const bf16x8*)(arow + k0), w0 = *(const bf16x8*)(b0 + k0), w1 = *(const bf16x8*)(b1 + k0);
;         acc[0] = mfma16(w0, af, acc[0]); acc[1] = mfma16(w1, af, acc[1]);
;     }
; }
; DEVI void mini_mix_tile(const Params& p, const int t) {
;     ...
;     mini_kloop(OB + (size_t)tok * 512 + 8 * g, WBT + (size_t)(colw + l15) * 512 + 8 * g, WBT + (size_t)(colw + 16 + l15) * 512 + 8 * g, 512, ab);
	s_waitcnt lgkmcnt(3)
	ds_bpermute_b32 v172, v45, v100
	ds_bpermute_b32 v173, v45, v101
	ds_bpermute_b32 v174, v45, v102
	ds_bpermute_b32 v175, v45, v103
	ds_bpermute_b32 v176, v45, v104
	ds_bpermute_b32 v177, v45, v105
	ds_bpermute_b32 v178, v45, v106
	ds_bpermute_b32 v179, v45, v107
	ds_bpermute_b32 v180, v45, v108
	ds_bpermute_b32 v181, v45, v109
	ds_bpermute_b32 v182, v45, v110
	ds_bpermute_b32 v183, v45, v111
	s_waitcnt lgkmcnt(12)
	v_mfma_f32_16x16x32_bf16 v[12:15], v[164:167], v[160:163], v[12:15]
	v_mfma_f32_16x16x32_bf16 v[8:11], v[168:171], v[160:163], v[8:11]
	global_load_dwordx4 v[88:91], v[34:35], off offset:640
	global_load_dwordx4 v[92:95], v[36:37], off offset:640
	global_load_dwordx4 v[96:99], v[38:39], off offset:640
	s_waitcnt vmcnt(18)
	s_waitcnt lgkmcnt(3)
	ds_bpermute_b32 v160, v45, v112
	ds_bpermute_b32 v161, v45, v113
	ds_bpermute_b32 v162, v45, v114
	ds_bpermute_b32 v163, v45, v115
	ds_bpermute_b32 v164, v45, v116
	ds_bpermute_b32 v165, v45, v117
	ds_bpermute_b32 v166, v45, v118
	ds_bpermute_b32 v167, v45, v119
	ds_bpermute_b32 v168, v45, v120
	ds_bpermute_b32 v169, v45, v121
	ds_bpermute_b32 v170, v45, v122
	ds_bpermute_b32 v171, v45, v123
	s_waitcnt lgkmcnt(12)
	v_mfma_f32_16x16x32_bf16 v[12:15], v[176:179], v[172:175], v[12:15]
	v_mfma_f32_16x16x32_bf16 v[8:11], v[180:183], v[172:175], v[8:11]
	global_load_dwordx4 v[100:103], v[34:35], off offset:704
	global_load_dwordx4 v[104:107], v[36:37], off offset:704
	global_load_dwordx4 v[108:111], v[38:39], off offset:704
	s_waitcnt vmcnt(18)
	s_waitcnt lgkmcnt(3)
	ds_bpermute_b32 v172, v45, v124
	ds_bpermute_b32 v173, v45, v125
	ds_bpermute_b32 v174, v45, v126
	ds_bpermute_b32 v175, v45, v127
	ds_bpermute_b32 v176, v45, v128
	ds_bpermute_b32 v177, v45, v129
	ds_bpermute_b32 v178, v45, v130
	ds_bpermute_b32 v179, v45, v131
	ds_bpermute_b32 v180, v45, v132
	ds_bpermute_b32 v181, v45, v133
	ds_bpermute_b32 v182, v45, v134
	ds_bpermute_b32 v183, v45, v135
	s_waitcnt lgkmcnt(12)
	v_mfma_f32_16x16x32_bf16 v[12:15], v[164:167], v[160:163], v[12:15]
	v_mfma_f32_16x16x32_bf16 v[8:11], v[168:171], v[160:163], v[8:11]
	global_load_dwordx4 v[112:115], v[34:35], off offset:768
	global_load_dwordx4 v[116:119], v[36:37], off offset:768
	global_load_dwordx4 v[120:123], v[38:39], off offset:768
	s_waitcnt vmcnt(18)
	s_waitcnt lgkmcnt(3)
	ds_bpermute_b32 v160, v45, v136
	ds_bpermute_b32 v161, v45, v137
	ds_bpermute_b32 v162, v45, v138
	ds_bpermute_b32 v163, v45, v139
	ds_bpermute_b32 v164, v45, v140
	ds_bpermute_b32 v165, v45, v141
	ds_bpermute_b32 v166, v45, v142
	ds_bpermute_b32 v167, v45, v143
	ds_bpermute_b32 v168, v45, v144
	ds_bpermute_b32 v169, v45, v145
	ds_bpermute_b32 v170, v45, v146
	ds_bpermute_b32 v171, v45, v147
	s_waitcnt lgkmcnt(12)
	v_mfma_f32_16x16x32_bf16 v[12:15], v[176:179], v[172:175], v[12:15]
	v_mfma_f32_16x16x32_bf16 v[8:11], v[180:183], v[172:175], v[8:11]
	global_load_dwordx4 v[124:127], v[34:35], off offset:832
	global_load_dwordx4 v[128:131], v[36:37], off offset:832
	global_load_dwordx4 v[132:135], v[38:39], off offset:832
	s_waitcnt vmcnt(18)
	s_waitcnt lgkmcnt(3)
	ds_bpermute_b32 v172, v45, v148
	ds_bpermute_b32 v173, v45, v149
	ds_bpermute_b32 v174, v45, v150
	ds_bpermute_b32 v175, v45, v151
	ds_bpermute_b32 v176, v45, v152
	ds_bpermute_b32 v177, v45, v153
	ds_bpermute_b32 v178, v45, v154
	ds_bpermute_b32 v179, v45, v155
	ds_bpermute_b32 v180, v45, v156
	ds_bpermute_b32 v181, v45, v157
	ds_bpermute_b32 v182, v45, v158
	ds_bpermute_b32 v183, v45, v159
	s_waitcnt lgkmcnt(12)
	v_mfma_f32_16x16x32_bf16 v[12:15], v[164:167], v[160:163], v[12:15]
	v_mfma_f32_16x16x32_bf16 v[8:11], v[168:171], v[160:163], v[8:11]
	global_load_dwordx4 v[136:139], v[34:35], off offset:896
	global_load_dwordx4 v[140:143], v[36:37], off offset:896
	global_load_dwordx4 v[144:147], v[38:39], off offset:896
	s_waitcnt vmcnt(18)
	s_waitcnt lgkmcnt(3)
	ds_bpermute_b32 v160, v45, v64
	ds_bpermute_b32 v161, v45, v65
	ds_bpermute_b32 v162, v45, v66
	ds_bpermute_b32 v163, v45, v67
	ds_bpermute_b32 v164, v45, v68
	ds_bpermute_b32 v165, v45, v69
	ds_bpermute_b32 v166, v45, v70
	ds_bpermute_b32 v167, v45, v71
	ds_bpermute_b32 v168, v45, v72
	ds_bpermute_b32 v169, v45, v73
	ds_bpermute_b32 v170, v45, v74
	ds_bpermute_b32 v171, v45, v75
	s_waitcnt lgkmcnt(12)
	v_mfma_f32_16x16x32_bf16 v[12:15], v[176:179], v[172:175], v[12:15]
	v_mfma_f32_16x16x32_bf16 v[8:11], v[180:183], v[172:175], v[8:11]
	global_load_dwordx4 v[148:151], v[34:35], off offset:960
	global_load_dwordx4 v[152:155], v[36:37], off offset:960
	global_load_dwordx4 v[156:159], v[38:39], off offset:960
	s_waitcnt vmcnt(18)
	s_waitcnt lgkmcnt(3)
	ds_bpermute_b32 v172, v45, v76
	ds_bpermute_b32 v173, v45, v77
	ds_bpermute_b32 v174, v45, v78
	ds_bpermute_b32 v175, v45, v79
	ds_bpermute_b32 v176, v45, v80
	ds_bpermute_b32 v177, v45, v81
	ds_bpermute_b32 v178, v45, v82
	ds_bpermute_b32 v179, v45, v83
	ds_bpermute_b32 v180, v45, v84
	ds_bpermute_b32 v181, v45, v85
	ds_bpermute_b32 v182, v45, v86
	ds_bpermute_b32 v183, v45, v87
	s_waitcnt lgkmcnt(12)
	v_mfma_f32_16x16x32_bf16 v[12:15], v[164:167], v[160:163], v[12:15]
	v_mfma_f32_16x16x32_bf16 v[8:11], v[168:171], v[160:163], v[8:11]
	s_waitcnt vmcnt(15)
	s_waitcnt lgkmcnt(3)
	ds_bpermute_b32 v160, v45, v88
	ds_bpermute_b32 v161, v45, v89
	ds_bpermute_b32 v162, v45, v90
	ds_bpermute_b32 v163, v45, v91
	ds_bpermute_b32 v164, v45, v92
	ds_bpermute_b32 v165, v45, v93
	ds_bpermute_b32 v166, v45, v94
	ds_bpermute_b32 v167, v45, v95
	ds_bpermute_b32 v168, v45, v96
	ds_bpermute_b32 v169, v45, v97
	ds_bpermute_b32 v170, v45, v98
	ds_bpermute_b32 v171, v45, v99
	s_waitcnt lgkmcnt(12)
; DEVI unsigned pk_bf16(float lo, float hi) { const f32x2_t v = {lo, hi}; const bf16x2_t b = __builtin_convertvector(v, bf16x2_t); return __builtin_bit_cast(unsigned, b); }
; DEVI float bf_lo(unsigned u) { return __uint_as_float(u << 16); }
; DEVI float bf_hi(unsigned u) { return __uint_as_float(u & 0xffff0000u); }
; DEVI f32x4 mfma16(bf16x8 a, bf16x8 b, f32x4 c) { return __builtin_amdgcn_mfma_f32_16x16x32_bf16(a, b, c, 0, 0, 0); }
; DEVI void mini_kloop(const bf16_t* __restrict__ arow, const bf16_t* __restrict__ b0, const bf16_t* __restrict__ b1, const int K, f32x4 (&acc)[2]) {
; #pragma unroll 8
;     for (int k0 = 0; k0 < K; k0 += 32) {
;         const bf16x8 af = *(const bf16x8*)(arow + k0), w0 = *(const bf16x8*)(b0 + k0), w1 = *(const bf16x8*)(b1 + k0);
;         acc[0] = mfma16(w0, af, acc[0]); acc[1] = mfma16(w1, af, acc[1]);
;     }
; }
; DEVI void mini_mix_tile(const Params& p, const int t) {
;     ...
;     const bf16_t* G = (const bf16_t*)p.out; bf16_t* MX = (bf16_t*)(p.ws + W_XN);
; #pragma unroll
;     for (int tt = 0; tt < 2; ++tt) {
;         const int col = colw + 16 * tt + 4 * g;
;         const u32x2 ga = *(const u32x2*)(G + (size_t)tok * 2048 + col), gb = *(const u32x2*)(G + (size_t)tok * 2048 + 1024 + col);
;         f32x4 m;
;         m[0] = aa[tt][0] * bf_lo(ga.x) + ab[tt][0] * bf_lo(gb.x); m[1] = aa[tt][1] * bf_hi(ga.x) + ab[tt][1] * bf_hi(gb.x);
;         m[2] = aa[tt][2] * bf_lo(ga.y) + ab[tt][2] * bf_lo(gb.y); m[3] = aa[tt][3] * bf_hi(ga.y) + ab[tt][3] * bf_hi(gb.y);
;         u32x2 o; o.x = pk_bf16(m[0], m[1]); o.y = pk_bf16(m[2], m[3]);
;         *(u32x2*)(MX + (size_t)tok * 1024 + col) = o;
;     }
	v_mfma_f32_16x16x32_bf16 v[12:15], v[176:179], v[172:175], v[12:15]
	v_mfma_f32_16x16x32_bf16 v[8:11], v[180:183], v[172:175], v[8:11]
	s_waitcnt vmcnt(12)
	s_waitcnt lgkmcnt(3)
	ds_bpermute_b32 v172, v45, v100
	ds_bpermute_b32 v173, v45, v101
	ds_bpermute_b32 v174, v45, v102
	ds_bpermute_b32 v175, v45, v103
	ds_bpermute_b32 v176, v45, v104
	ds_bpermute_b32 v177, v45, v105
	ds_bpermute_b32 v178, v45, v106
	ds_bpermute_b32 v179, v45, v107
	ds_bpermute_b32 v180, v45, v108
	ds_bpermute_b32 v181, v45, v109
	ds_bpermute_b32 v182, v45, v110
	ds_bpermute_b32 v183, v45, v111
	s_waitcnt lgkmcnt(12)
	v_mfma_f32_16x16x32_bf16 v[12:15], v[164:167], v[160:163], v[12:15]
	v_mfma_f32_16x16x32_bf16 v[8:11], v[168:171], v[160:163], v[8:11]
	s_waitcnt vmcnt(9)
	s_waitcnt lgkmcnt(3)
	ds_bpermute_b32 v160, v45, v112
	ds_bpermute_b32 v161, v45, v113
	ds_bpermute_b32 v162, v45, v114
	ds_bpermute_b32 v163, v45, v115
	ds_bpermute_b32 v164, v45, v116
	ds_bpermute_b32 v165, v45, v117
	ds_bpermute_b32 v166, v45, v118
	ds_bpermute_b32 v167, v45, v119
	ds_bpermute_b32 v168, v45, v120
	ds_bpermute_b32 v169, v45, v121
	ds_bpermute_b32 v170, v45, v122
	ds_bpermute_b32 v171, v45, v123
	s_waitcnt lgkmcnt(12)
	v_mfma_f32_16x16x32_bf16 v[12:15], v[176:179], v[172:175], v[12:15]
	v_mfma_f32_16x16x32_bf16 v[8:11], v[180:183], v[172:175], v[8:11]
	s_waitcnt vmcnt(6)
	s_waitcnt lgkmcnt(3)
	ds_bpermute_b32 v172, v45, v124
	ds_bpermute_b32 v173, v45, v125
	ds_bpermute_b32 v174, v45, v126
	ds_bpermute_b32 v175, v45, v127
	ds_bpermute_b32 v176, v45, v128
	ds_bpermute_b32 v177, v45, v129
	ds_bpermute_b32 v178, v45, v130
	ds_bpermute_b32 v179, v45, v131
	ds_bpermute_b32 v180, v45, v132
	ds_bpermute_b32 v181, v45, v133
	ds_bpermute_b32 v182, v45, v134
	ds_bpermute_b32 v183, v45, v135
	s_waitcnt lgkmcnt(12)
	v_mfma_f32_16x16x32_bf16 v[12:15], v[164:167], v[160:163], v[12:15]
	v_mfma_f32_16x16x32_bf16 v[8:11], v[168:171], v[160:163], v[8:11]
	s_waitcnt vmcnt(3)
	s_waitcnt lgkmcnt(3)
	ds_bpermute_b32 v160, v45, v136
	ds_bpermute_b32 v161, v45, v137
	ds_bpermute_b32 v162, v45, v138
	ds_bpermute_b32 v163, v45, v139
	ds_bpermute_b32 v164, v45, v140
	ds_bpermute_b32 v165, v45, v141
	ds_bpermute_b32 v166, v45, v142
	ds_bpermute_b32 v167, v45, v143
	ds_bpermute_b32 v168, v45, v144
	ds_bpermute_b32 v169, v45, v145
	ds_bpermute_b32 v170, v45, v146
	ds_bpermute_b32 v171, v45, v147
	s_waitcnt lgkmcnt(12)
	v_mfma_f32_16x16x32_bf16 v[12:15], v[176:179], v[172:175], v[12:15]
	v_mfma_f32_16x16x32_bf16 v[8:11], v[180:183], v[172:175], v[8:11]
	s_waitcnt vmcnt(0)
	s_waitcnt lgkmcnt(3)
	ds_bpermute_b32 v172, v45, v148
	ds_bpermute_b32 v173, v45, v149
	ds_bpermute_b32 v174, v45, v150
	ds_bpermute_b32 v175, v45, v151
	ds_bpermute_b32 v176, v45, v152
	ds_bpermute_b32 v177, v45, v153
	ds_bpermute_b32 v178, v45, v154
	ds_bpermute_b32 v179, v45, v155
	ds_bpermute_b32 v180, v45, v156
	ds_bpermute_b32 v181, v45, v157
	ds_bpermute_b32 v182, v45, v158
	ds_bpermute_b32 v183, v45, v159
	s_waitcnt lgkmcnt(12)
	v_mfma_f32_16x16x32_bf16 v[12:15], v[164:167], v[160:163], v[12:15]
	v_mfma_f32_16x16x32_bf16 v[8:11], v[168:171], v[160:163], v[8:11]
	s_waitcnt lgkmcnt(0)
	v_mfma_f32_16x16x32_bf16 v[12:15], v[176:179], v[172:175], v[12:15]
	v_mfma_f32_16x16x32_bf16 v[8:11], v[180:183], v[172:175], v[8:11]
	s_lshl_b32 s3, s7, 2
	s_andn2_b32 s3, s3, 63
	s_add_i32 s3, s3, 0x8000
	v_or3_b32 v18, v25, s3, v24
	s_lshl_b32 s3, s7, 6
	s_and_b32 s3, s3, 0x3c0
	v_and_b32_e32 v16, 3, v27
	v_add_u32_e32 v20, s3, v26
	v_ashrrev_i32_e32 v19, 31, v18
	v_lshl_or_b32 v20, v16, 2, v20
	v_readlane_b32 s12, v234, 24
	v_lshlrev_b64 v[22:23], 12, v[18:19]
	v_readlane_b32 s26, v234, 38
	v_readlane_b32 s27, v234, 39
	v_ashrrev_i32_e32 v21, 31, v20
	v_lshlrev_b64 v[20:21], 1, v[20:21]
	v_lshl_add_u64 v[22:23], s[26:27], 0, v[22:23]
	v_lshl_add_u64 v[22:23], v[22:23], 0, v[20:21]
	global_load_dwordx2 v[24:25], v[22:23], off
	global_load_dwordx2 v[26:27], v[22:23], off offset:2048
	v_lshlrev_b64 v[18:19], 11, v[18:19]
	v_lshl_add_u64 v[18:19], s[88:89], 0, v[18:19]
	v_lshl_add_u64 v[18:19], v[18:19], 0, v[20:21]
	s_add_i32 s7, s7, s97
	s_add_i32 s2, s2, s4
	s_add_i32 s5, s5, s6
	s_cmpk_gt_i32 s7, 0xff
	v_readlane_b32 s13, v234, 25
	v_readlane_b32 s14, v234, 26
	v_readlane_b32 s15, v234, 27
	v_readlane_b32 s16, v234, 28
	v_readlane_b32 s17, v234, 29
	v_readlane_b32 s18, v234, 30
	v_readlane_b32 s19, v234, 31
	v_readlane_b32 s20, v234, 32
	v_readlane_b32 s21, v234, 33
	v_readlane_b32 s22, v234, 34
	v_readlane_b32 s23, v234, 35
	v_readlane_b32 s24, v234, 36
	v_readlane_b32 s25, v234, 37
	s_waitcnt vmcnt(1)
	v_lshlrev_b32_e32 v20, 16, v24
	s_waitcnt vmcnt(0)
	v_lshlrev_b32_e32 v28, 16, v26
	v_and_b32_e32 v29, 0xffff0000, v26
	v_lshlrev_b32_e32 v26, 16, v27
	v_and_b32_e32 v27, 0xffff0000, v27
	v_and_b32_e32 v21, 0xffff0000, v24
	v_lshlrev_b32_e32 v24, 16, v25
	v_and_b32_e32 v25, 0xffff0000, v25
	v_pk_mul_f32 v[12:13], v[12:13], v[28:29]
	v_pk_mul_f32 v[14:15], v[14:15], v[26:27]
	v_pk_fma_f32 v[4:5], v[4:5], v[20:21], v[12:13]
	v_pk_fma_f32 v[6:7], v[6:7], v[24:25], v[14:15]
	v_cvt_pk_bf16_f32 v4, v4, v5
	v_cvt_pk_bf16_f32 v5, v6, v7
	global_store_dwordx2 v[18:19], v[4:5], off
	global_load_dwordx2 v[4:5], v[22:23], off offset:32
	s_nop 0
	global_load_dwordx2 v[6:7], v[22:23], off offset:2080
	s_waitcnt vmcnt(1)
	v_lshlrev_b32_e32 v12, 16, v4
	s_waitcnt vmcnt(0)
	v_lshlrev_b32_e32 v14, 16, v6
	v_and_b32_e32 v15, 0xffff0000, v6
	v_lshlrev_b32_e32 v6, 16, v7
	v_and_b32_e32 v7, 0xffff0000, v7
	v_and_b32_e32 v13, 0xffff0000, v4
	v_lshlrev_b32_e32 v4, 16, v5
	v_and_b32_e32 v5, 0xffff0000, v5
	v_pk_mul_f32 v[8:9], v[8:9], v[14:15]
	v_pk_mul_f32 v[6:7], v[10:11], v[6:7]
	v_pk_fma_f32 v[0:1], v[0:1], v[12:13], v[8:9]
	v_pk_fma_f32 v[2:3], v[2:3], v[4:5], v[6:7]
	v_cvt_pk_bf16_f32 v0, v0, v1
	v_cvt_pk_bf16_f32 v1, v2, v3
	global_store_dwordx2 v[18:19], v[0:1], off offset:32
	s_cbranch_scc0 .LBB0_994

; DEVI f32x4 mfma16(bf16x8 a, bf16x8 b, f32x4 c) { return __builtin_amdgcn_mfma_f32_16x16x32_bf16(a, b, c, 0, 0, 0); }
; DEVI void mini_kloop(const bf16_t* __restrict__ arow, const bf16_t* __restrict__ b0, const bf16_t* __restrict__ b1, const int K, f32x4 (&acc)[2]) {
; #pragma unroll 8
;     for (int k0 = 0; k0 < K; k0 += 32) {
;         const bf16x8 af = *(const bf16x8*)(arow + k0), w0 = *(const bf16x8*)(b0 + k0), w1 = *(const bf16x8*)(b1 + k0);
;         acc[0] = mfma16(w0, af, acc[0]); acc[1] = mfma16(w1, af, acc[1]);
;     }
; }
; DEVI void mini_y_tile(const Params& p, const int t) {
;     int tid = threadIdx.x; asm volatile("" : "+v"(tid));
;     const int lane = tid & 63, w = tid >> 6, l15 = lane & 15, g = lane >> 4;
;     const int tok = NTP + 64 * (t >> 4) + 16 * (w & 3) + l15, colw = 64 * (t & 15) + 32 * (w >> 2);
;     const bf16_t* MX = (const bf16_t*)(p.ws + W_XN); const bf16_t* WOT = (const bf16_t*)(p.ws + W_WOT);
;     f32x4 acc[2] = {(f32x4){0.f, 0.f, 0.f, 0.f}, (f32x4){0.f, 0.f, 0.f, 0.f}};
;     mini_kloop(MX + (size_t)tok * 1024 + 8 * g, WOT + (size_t)(colw + l15) * 1024 + 8 * g, WOT + (size_t)(colw + 16 + l15) * 1024 + 8 * g, 1024, acc);
.LBB0_1208:
	v_lshl_add_u64 v[20:21], v[12:13], 0, v[8:9]
	v_lshl_add_u64 v[22:23], v[14:15], 0, v[8:9]
	v_lshl_add_u64 v[24:25], v[10:11], 0, v[8:9]
	v_add_co_u32_e32 v22, vcc, s9, v22
	s_nop 1
	v_addc_co_u32_e32 v23, vcc, 0, v23, vcc
	v_add_co_u32_e32 v24, vcc, s9, v24
	s_nop 1
	v_addc_co_u32_e32 v25, vcc, 0, v25, vcc
	v_and_b32_e32 v40, 63, v203
	v_and_b32_e32 v41, 3, v40
	v_lshrrev_b32_e32 v42, 4, v40
	v_bfe_u32 v43, v40, 2, 2
	v_lshl_add_u32 v44, v42, 2, v43
	v_lshl_add_u32 v44, v41, 4, v44
	v_lshlrev_b32_e32 v44, 2, v44
	v_lshlrev_b32_e32 v45, 4, v43
	v_lshl_add_u32 v45, v41, 2, v45
	v_add_u32_e32 v45, v45, v42
	v_lshlrev_b32_e32 v45, 2, v45
	ds_bpermute_b32 v20, v44, v20
	ds_bpermute_b32 v21, v44, v21
	ds_bpermute_b32 v22, v44, v22
	ds_bpermute_b32 v23, v44, v23
	ds_bpermute_b32 v24, v44, v24
	ds_bpermute_b32 v25, v44, v25
	s_waitcnt lgkmcnt(0)
	global_load_dwordx4 v[64:67], v[20:21], off
	global_load_dwordx4 v[68:71], v[22:23], off
	global_load_dwordx4 v[72:75], v[24:25], off
	global_load_dwordx4 v[76:79], v[20:21], off offset:64
	global_load_dwordx4 v[80:83], v[22:23], off offset:64
	global_load_dwordx4 v[84:87], v[24:25], off offset:64
	global_load_dwordx4 v[88:91], v[20:21], off offset:128
	global_load_dwordx4 v[92:95], v[22:23], off offset:128
	global_load_dwordx4 v[96:99], v[24:25], off offset:128
	global_load_dwordx4 v[100:103], v[20:21], off offset:192
	global_load_dwordx4 v[104:107], v[22:23], off offset:192
	global_load_dwordx4 v[108:111], v[24:25], off offset:192
	global_load_dwordx4 v[112:115], v[20:21], off offset:256
	global_load_dwordx4 v[116:119], v[22:23], off offset:256
	global_load_dwordx4 v[120:123], v[24:25], off offset:256
	global_load_dwordx4 v[124:127], v[20:21], off offset:320
	global_load_dwordx4 v[128:131], v[22:23], off offset:320
	global_load_dwordx4 v[132:135], v[24:25], off offset:320
	global_load_dwordx4 v[136:139], v[20:21], off offset:384
	global_load_dwordx4 v[140:143], v[22:23], off offset:384
	global_load_dwordx4 v[144:147], v[24:25], off offset:384
	global_load_dwordx4 v[148:151], v[20:21], off offset:448
	global_load_dwordx4 v[152:155], v[22:23], off offset:448
	global_load_dwordx4 v[156:159], v[24:25], off offset:448
	s_waitcnt vmcnt(21)
	ds_bpermute_b32 v160, v45, v64
	ds_bpermute_b32 v161, v45, v65
	ds_bpermute_b32 v162, v45, v66
	ds_bpermute_b32 v163, v45, v67
	ds_bpermute_b32 v164, v45, v68
	ds_bpermute_b32 v165, v45, v69
	ds_bpermute_b32 v166, v45, v70
	ds_bpermute_b32 v167, v45, v71
	ds_bpermute_b32 v168, v45, v72
	ds_bpermute_b32 v169, v45, v73
	ds_bpermute_b32 v170, v45, v74
	ds_bpermute_b32 v171, v45, v75
	s_waitcnt vmcnt(18)
	s_waitcnt lgkmcnt(3)
	ds_bpermute_b32 v172, v45, v76
	ds_bpermute_b32 v173, v45, v77
	ds_bpermute_b32 v174, v45, v78
	ds_bpermute_b32 v175, v45, v79
	ds_bpermute_b32 v176, v45, v80
	ds_bpermute_b32 v177, v45, v81
	ds_bpermute_b32 v178, v45, v82
	ds_bpermute_b32 v179, v45, v83
	ds_bpermute_b32 v180, v45, v84
	ds_bpermute_b32 v181, v45, v85
	ds_bpermute_b32 v182, v45, v86
	ds_bpermute_b32 v183, v45, v87
	s_waitcnt lgkmcnt(12)
	v_mfma_f32_16x16x32_bf16 v[4:7], v[164:167], v[160:163], v[4:7]
	v_mfma_f32_16x16x32_bf16 v[0:3], v[168:171], v[160:163], v[0:3]
	global_load_dwordx4 v[64:67], v[20:21], off offset:512
	global_load_dwordx4 v[68:71], v[22:23], off offset:512
	global_load_dwordx4 v[72:75], v[24:25], off offset:512
	s_waitcnt vmcnt(18)
	s_waitcnt lgkmcnt(3)
	ds_bpermute_b32 v160, v45, v88
	ds_bpermute_b32 v161, v45, v89
	ds_bpermute_b32 v162, v45, v90
	ds_bpermute_b32 v163, v45, v91
	ds_bpermute_b32 v164, v45, v92
	ds_bpermute_b32 v165, v45, v93
	ds_bpermute_b32 v166, v45, v94
	ds_bpermute_b32 v167, v45, v95
	ds_bpermute_b32 v168, v45, v96
	ds_bpermute_b32 v169, v45, v97
	ds_bpermute_b32 v170, v45, v98
	ds_bpermute_b32 v171, v45, v99
	s_waitcnt lgkmcnt(12)
	v_mfma_f32_16x16x32_bf16 v[4:7], v[176:179], v[172:175], v[4:7]
	v_mfma_f32_16x16x32_bf16 v[0:3], v[180:183], v[172:175], v[0:3]
	global_load_dwordx4 v[76:79], v[20:21], off offset:576
	global_load_dwordx4 v[80:83], v[22:23], off offset:576
	global_load_dwordx4 v[84:87], v[24:25], off offset:576
	s_waitcnt vmcnt(18)
	s_waitcnt lgkmcnt(3)
	ds_bpermute_b32 v172, v45, v100
	ds_bpermute_b32 v173, v45, v101
	ds_bpermute_b32 v174, v45, v102
	ds_bpermute_b32 v175, v45, v103
	ds_bpermute_b32 v176, v45, v104
	ds_bpermute_b32 v177, v45, v105
	ds_bpermute_b32 v178, v45, v106
	ds_bpermute_b32 v179, v45, v107
	ds_bpermute_b32 v180, v45, v108
	ds_bpermute_b32 v181, v45, v109
	ds_bpermute_b32 v182, v45, v110
	ds_bpermute_b32 v183, v45, v111
	s_waitcnt lgkmcnt(12)
	v_mfma_f32_16x16x32_bf16 v[4:7], v[164:167], v[160:163], v[4:7]
	v_mfma_f32_16x16x32_bf16 v[0:3], v[168:171], v[160:163], v[0:3]
	global_load_dwordx4 v[88:91], v[20:21], off offset:640
	global_load_dwordx4 v[92:95], v[22:23], off offset:640
	global_load_dwordx4 v[96:99], v[24:25], off offset:640
	s_waitcnt vmcnt(18)
	s_waitcnt lgkmcnt(3)
	ds_bpermute_b32 v160, v45, v112
	ds_bpermute_b32 v161, v45, v113
	ds_bpermute_b32 v162, v45, v114
	ds_bpermute_b32 v163, v45, v115
	ds_bpermute_b32 v164, v45, v116
	ds_bpermute_b32 v165, v45, v117
	ds_bpermute_b32 v166, v45, v118
	ds_bpermute_b32 v167, v45, v119
	ds_bpermute_b32 v168, v45, v120
	ds_bpermute_b32 v169, v45, v121
	ds_bpermute_b32 v170, v45, v122
	ds_bpermute_b32 v171, v45, v123
	s_waitcnt lgkmcnt(12)
	v_mfma_f32_16x16x32_bf16 v[4:7], v[176:179], v[172:175], v[4:7]
	v_mfma_f32_16x16x32_bf16 v[0:3], v[180:183], v[172:175], v[0:3]
	global_load_dwordx4 v[100:103], v[20:21], off offset:704
	global_load_dwordx4 v[104:107], v[22:23], off offset:704
	global_load_dwordx4 v[108:111], v[24:25], off offset:704
	s_waitcnt vmcnt(18)
; DEVI f32x4 mfma16(bf16x8 a, bf16x8 b, f32x4 c) { return __builtin_amdgcn_mfma_f32_16x16x32_bf16(a, b, c, 0, 0, 0); }
; DEVI void mini_kloop(const bf16_t* __restrict__ arow, const bf16_t* __restrict__ b0, const bf16_t* __restrict__ b1, const int K, f32x4 (&acc)[2]) {
; #pragma unroll 8
;     for (int k0 = 0; k0 < K; k0 += 32) {
;         const bf16x8 af = *(const bf16x8*)(arow + k0), w0 = *(const bf16x8*)(b0 + k0), w1 = *(const bf16x8*)(b1 + k0);
;         acc[0] = mfma16(w0, af, acc[0]); acc[1] = mfma16(w1, af, acc[1]);
;     }
; }
; DEVI void mini_y_tile(const Params& p, const int t) {
;     ...
;     mini_kloop(MX + (size_t)tok * 1024 + 8 * g, WOT + (size_t)(colw + l15) * 1024 + 8 * g, WOT + (size_t)(colw + 16 + l15) * 1024 + 8 * g, 1024, acc);
	s_waitcnt lgkmcnt(3)
	ds_bpermute_b32 v172, v45, v124
	ds_bpermute_b32 v173, v45, v125
	ds_bpermute_b32 v174, v45, v126
	ds_bpermute_b32 v175, v45, v127
	ds_bpermute_b32 v176, v45, v128
	ds_bpermute_b32 v177, v45, v129
	ds_bpermute_b32 v178, v45, v130
	ds_bpermute_b32 v179, v45, v131
	ds_bpermute_b32 v180, v45, v132
	ds_bpermute_b32 v181, v45, v133
	ds_bpermute_b32 v182, v45, v134
	ds_bpermute_b32 v183, v45, v135
	s_waitcnt lgkmcnt(12)
	v_mfma_f32_16x16x32_bf16 v[4:7], v[164:167], v[160:163], v[4:7]
	v_mfma_f32_16x16x32_bf16 v[0:3], v[168:171], v[160:163], v[0:3]
	global_load_dwordx4 v[112:115], v[20:21], off offset:768
	global_load_dwordx4 v[116:119], v[22:23], off offset:768
	global_load_dwordx4 v[120:123], v[24:25], off offset:768
	s_waitcnt vmcnt(18)
	s_waitcnt lgkmcnt(3)
	ds_bpermute_b32 v160, v45, v136
	ds_bpermute_b32 v161, v45, v137
	ds_bpermute_b32 v162, v45, v138
	ds_bpermute_b32 v163, v45, v139
	ds_bpermute_b32 v164, v45, v140
	ds_bpermute_b32 v165, v45, v141
	ds_bpermute_b32 v166, v45, v142
	ds_bpermute_b32 v167, v45, v143
	ds_bpermute_b32 v168, v45, v144
	ds_bpermute_b32 v169, v45, v145
	ds_bpermute_b32 v170, v45, v146
	ds_bpermute_b32 v171, v45, v147
	s_waitcnt lgkmcnt(12)
	v_mfma_f32_16x16x32_bf16 v[4:7], v[176:179], v[172:175], v[4:7]
	v_mfma_f32_16x16x32_bf16 v[0:3], v[180:183], v[172:175], v[0:3]
	global_load_dwordx4 v[124:127], v[20:21], off offset:832
	global_load_dwordx4 v[128:131], v[22:23], off offset:832
	global_load_dwordx4 v[132:135], v[24:25], off offset:832
	s_waitcnt vmcnt(18)
	s_waitcnt lgkmcnt(3)
	ds_bpermute_b32 v172, v45, v148
	ds_bpermute_b32 v173, v45, v149
	ds_bpermute_b32 v174, v45, v150
	ds_bpermute_b32 v175, v45, v151
	ds_bpermute_b32 v176, v45, v152
	ds_bpermute_b32 v177, v45, v153
	ds_bpermute_b32 v178, v45, v154
	ds_bpermute_b32 v179, v45, v155
	ds_bpermute_b32 v180, v45, v156
	ds_bpermute_b32 v181, v45, v157
	ds_bpermute_b32 v182, v45, v158
	ds_bpermute_b32 v183, v45, v159
	s_waitcnt lgkmcnt(12)
	v_mfma_f32_16x16x32_bf16 v[4:7], v[164:167], v[160:163], v[4:7]
	v_mfma_f32_16x16x32_bf16 v[0:3], v[168:171], v[160:163], v[0:3]
	global_load_dwordx4 v[136:139], v[20:21], off offset:896
	global_load_dwordx4 v[140:143], v[22:23], off offset:896
	global_load_dwordx4 v[144:147], v[24:25], off offset:896
	s_waitcnt vmcnt(18)
	s_waitcnt lgkmcnt(3)
	ds_bpermute_b32 v160, v45, v64
	ds_bpermute_b32 v161, v45, v65
	ds_bpermute_b32 v162, v45, v66
	ds_bpermute_b32 v163, v45, v67
	ds_bpermute_b32 v164, v45, v68
	ds_bpermute_b32 v165, v45, v69
	ds_bpermute_b32 v166, v45, v70
	ds_bpermute_b32 v167, v45, v71
	ds_bpermute_b32 v168, v45, v72
	ds_bpermute_b32 v169, v45, v73
	ds_bpermute_b32 v170, v45, v74
	ds_bpermute_b32 v171, v45, v75
	s_waitcnt lgkmcnt(12)
	v_mfma_f32_16x16x32_bf16 v[4:7], v[176:179], v[172:175], v[4:7]
	v_mfma_f32_16x16x32_bf16 v[0:3], v[180:183], v[172:175], v[0:3]
	global_load_dwordx4 v[148:151], v[20:21], off offset:960
	global_load_dwordx4 v[152:155], v[22:23], off offset:960
	global_load_dwordx4 v[156:159], v[24:25], off offset:960
	s_waitcnt vmcnt(18)
	s_waitcnt lgkmcnt(3)
	ds_bpermute_b32 v172, v45, v76
	ds_bpermute_b32 v173, v45, v77
	ds_bpermute_b32 v174, v45, v78
	ds_bpermute_b32 v175, v45, v79
	ds_bpermute_b32 v176, v45, v80
	ds_bpermute_b32 v177, v45, v81
	ds_bpermute_b32 v178, v45, v82
	ds_bpermute_b32 v179, v45, v83
	ds_bpermute_b32 v180, v45, v84
	ds_bpermute_b32 v181, v45, v85
	ds_bpermute_b32 v182, v45, v86
	ds_bpermute_b32 v183, v45, v87
	s_waitcnt lgkmcnt(12)
	v_mfma_f32_16x16x32_bf16 v[4:7], v[164:167], v[160:163], v[4:7]
	v_mfma_f32_16x16x32_bf16 v[0:3], v[168:171], v[160:163], v[0:3]
	global_load_dwordx4 v[64:67], v[20:21], off offset:1024
	global_load_dwordx4 v[68:71], v[22:23], off offset:1024
	global_load_dwordx4 v[72:75], v[24:25], off offset:1024
	s_waitcnt vmcnt(18)
	s_waitcnt lgkmcnt(3)
	ds_bpermute_b32 v160, v45, v88
	ds_bpermute_b32 v161, v45, v89
	ds_bpermute_b32 v162, v45, v90
	ds_bpermute_b32 v163, v45, v91
	ds_bpermute_b32 v164, v45, v92
	ds_bpermute_b32 v165, v45, v93
	ds_bpermute_b32 v166, v45, v94
	ds_bpermute_b32 v167, v45, v95
	ds_bpermute_b32 v168, v45, v96
	ds_bpermute_b32 v169, v45, v97
	ds_bpermute_b32 v170, v45, v98
	ds_bpermute_b32 v171, v45, v99
	s_waitcnt lgkmcnt(12)
	v_mfma_f32_16x16x32_bf16 v[4:7], v[176:179], v[172:175], v[4:7]
	v_mfma_f32_16x16x32_bf16 v[0:3], v[180:183], v[172:175], v[0:3]
	global_load_dwordx4 v[76:79], v[20:21], off offset:1088
	global_load_dwordx4 v[80:83], v[22:23], off offset:1088
	global_load_dwordx4 v[84:87], v[24:25], off offset:1088
	s_waitcnt vmcnt(18)
	s_waitcnt lgkmcnt(3)
	ds_bpermute_b32 v172, v45, v100
	ds_bpermute_b32 v173, v45, v101
	ds_bpermute_b32 v174, v45, v102
	ds_bpermute_b32 v175, v45, v103
	ds_bpermute_b32 v176, v45, v104
	ds_bpermute_b32 v177, v45, v105
	ds_bpermute_b32 v178, v45, v106
	ds_bpermute_b32 v179, v45, v107
	ds_bpermute_b32 v180, v45, v108
	ds_bpermute_b32 v181, v45, v109
	ds_bpermute_b32 v182, v45, v110
	ds_bpermute_b32 v183, v45, v111
	s_waitcnt lgkmcnt(12)
	v_mfma_f32_16x16x32_bf16 v[4:7], v[164:167], v[160:163], v[4:7]
	v_mfma_f32_16x16x32_bf16 v[0:3], v[168:171], v[160:163], v[0:3]
	global_load_dwordx4 v[88:91], v[20:21], off offset:1152
	global_load_dwordx4 v[92:95], v[22:23], off offset:1152
	global_load_dwordx4 v[96:99], v[24:25], off offset:1152
	s_waitcnt vmcnt(18)
	s_waitcnt lgkmcnt(3)
	ds_bpermute_b32 v160, v45, v112
	ds_bpermute_b32 v161, v45, v113
	ds_bpermute_b32 v162, v45, v114
	ds_bpermute_b32 v163, v45, v115
	ds_bpermute_b32 v164, v45, v116
	ds_bpermute_b32 v165, v45, v117
	ds_bpermute_b32 v166, v45, v118
	ds_bpermute_b32 v167, v45, v119
	ds_bpermute_b32 v168, v45, v120
	ds_bpermute_b32 v169, v45, v121
	ds_bpermute_b32 v170, v45, v122
	ds_bpermute_b32 v171, v45, v123
	s_waitcnt lgkmcnt(12)
; DEVI f32x4 mfma16(bf16x8 a, bf16x8 b, f32x4 c) { return __builtin_amdgcn_mfma_f32_16x16x32_bf16(a, b, c, 0, 0, 0); }
; DEVI void mini_kloop(const bf16_t* __restrict__ arow, const bf16_t* __restrict__ b0, const bf16_t* __restrict__ b1, const int K, f32x4 (&acc)[2]) {
; #pragma unroll 8
;     for (int k0 = 0; k0 < K; k0 += 32) {
;         const bf16x8 af = *(const bf16x8*)(arow + k0), w0 = *(const bf16x8*)(b0 + k0), w1 = *(const bf16x8*)(b1 + k0);
;         acc[0] = mfma16(w0, af, acc[0]); acc[1] = mfma16(w1, af, acc[1]);
;     }
; }
; DEVI void mini_y_tile(const Params& p, const int t) {
;     ...
;     mini_kloop(MX + (size_t)tok * 1024 + 8 * g, WOT + (size_t)(colw + l15) * 1024 + 8 * g, WOT + (size_t)(colw + 16 + l15) * 1024 + 8 * g, 1024, acc);
	v_mfma_f32_16x16x32_bf16 v[4:7], v[176:179], v[172:175], v[4:7]
	v_mfma_f32_16x16x32_bf16 v[0:3], v[180:183], v[172:175], v[0:3]
	global_load_dwordx4 v[100:103], v[20:21], off offset:1216
	global_load_dwordx4 v[104:107], v[22:23], off offset:1216
	global_load_dwordx4 v[108:111], v[24:25], off offset:1216
	s_waitcnt vmcnt(18)
	s_waitcnt lgkmcnt(3)
	ds_bpermute_b32 v172, v45, v124
	ds_bpermute_b32 v173, v45, v125
	ds_bpermute_b32 v174, v45, v126
	ds_bpermute_b32 v175, v45, v127
	ds_bpermute_b32 v176, v45, v128
	ds_bpermute_b32 v177, v45, v129
	ds_bpermute_b32 v178, v45, v130
	ds_bpermute_b32 v179, v45, v131
	ds_bpermute_b32 v180, v45, v132
	ds_bpermute_b32 v181, v45, v133
	ds_bpermute_b32 v182, v45, v134
	ds_bpermute_b32 v183, v45, v135
	s_waitcnt lgkmcnt(12)
	v_mfma_f32_16x16x32_bf16 v[4:7], v[164:167], v[160:163], v[4:7]
	v_mfma_f32_16x16x32_bf16 v[0:3], v[168:171], v[160:163], v[0:3]
	global_load_dwordx4 v[112:115], v[20:21], off offset:1280
	global_load_dwordx4 v[116:119], v[22:23], off offset:1280
	global_load_dwordx4 v[120:123], v[24:25], off offset:1280
	s_waitcnt vmcnt(18)
	s_waitcnt lgkmcnt(3)
	ds_bpermute_b32 v160, v45, v136
	ds_bpermute_b32 v161, v45, v137
	ds_bpermute_b32 v162, v45, v138
	ds_bpermute_b32 v163, v45, v139
	ds_bpermute_b32 v164, v45, v140
	ds_bpermute_b32 v165, v45, v141
	ds_bpermute_b32 v166, v45, v142
	ds_bpermute_b32 v167, v45, v143
	ds_bpermute_b32 v168, v45, v144
	ds_bpermute_b32 v169, v45, v145
	ds_bpermute_b32 v170, v45, v146
	ds_bpermute_b32 v171, v45, v147
	s_waitcnt lgkmcnt(12)
	v_mfma_f32_16x16x32_bf16 v[4:7], v[176:179], v[172:175], v[4:7]
	v_mfma_f32_16x16x32_bf16 v[0:3], v[180:183], v[172:175], v[0:3]
	global_load_dwordx4 v[124:127], v[20:21], off offset:1344
	global_load_dwordx4 v[128:131], v[22:23], off offset:1344
	global_load_dwordx4 v[132:135], v[24:25], off offset:1344
	s_waitcnt vmcnt(18)
	s_waitcnt lgkmcnt(3)
	ds_bpermute_b32 v172, v45, v148
	ds_bpermute_b32 v173, v45, v149
	ds_bpermute_b32 v174, v45, v150
	ds_bpermute_b32 v175, v45, v151
	ds_bpermute_b32 v176, v45, v152
	ds_bpermute_b32 v177, v45, v153
	ds_bpermute_b32 v178, v45, v154
	ds_bpermute_b32 v179, v45, v155
	ds_bpermute_b32 v180, v45, v156
	ds_bpermute_b32 v181, v45, v157
	ds_bpermute_b32 v182, v45, v158
	ds_bpermute_b32 v183, v45, v159
	s_waitcnt lgkmcnt(12)
	v_mfma_f32_16x16x32_bf16 v[4:7], v[164:167], v[160:163], v[4:7]
	v_mfma_f32_16x16x32_bf16 v[0:3], v[168:171], v[160:163], v[0:3]
	global_load_dwordx4 v[136:139], v[20:21], off offset:1408
	global_load_dwordx4 v[140:143], v[22:23], off offset:1408
	global_load_dwordx4 v[144:147], v[24:25], off offset:1408
	s_waitcnt vmcnt(18)
	s_waitcnt lgkmcnt(3)
	ds_bpermute_b32 v160, v45, v64
	ds_bpermute_b32 v161, v45, v65
	ds_bpermute_b32 v162, v45, v66
	ds_bpermute_b32 v163, v45, v67
	ds_bpermute_b32 v164, v45, v68
	ds_bpermute_b32 v165, v45, v69
	ds_bpermute_b32 v166, v45, v70
	ds_bpermute_b32 v167, v45, v71
	ds_bpermute_b32 v168, v45, v72
	ds_bpermute_b32 v169, v45, v73
	ds_bpermute_b32 v170, v45, v74
	ds_bpermute_b32 v171, v45, v75
	s_waitcnt lgkmcnt(12)
	v_mfma_f32_16x16x32_bf16 v[4:7], v[176:179], v[172:175], v[4:7]
	v_mfma_f32_16x16x32_bf16 v[0:3], v[180:183], v[172:175], v[0:3]
	global_load_dwordx4 v[148:151], v[20:21], off offset:1472
	global_load_dwordx4 v[152:155], v[22:23], off offset:1472
	global_load_dwordx4 v[156:159], v[24:25], off offset:1472
	s_waitcnt vmcnt(18)
	s_waitcnt lgkmcnt(3)
	ds_bpermute_b32 v172, v45, v76
	ds_bpermute_b32 v173, v45, v77
	ds_bpermute_b32 v174, v45, v78
	ds_bpermute_b32 v175, v45, v79
	ds_bpermute_b32 v176, v45, v80
	ds_bpermute_b32 v177, v45, v81
	ds_bpermute_b32 v178, v45, v82
	ds_bpermute_b32 v179, v45, v83
	ds_bpermute_b32 v180, v45, v84
	ds_bpermute_b32 v181, v45, v85
	ds_bpermute_b32 v182, v45, v86
	ds_bpermute_b32 v183, v45, v87
	s_waitcnt lgkmcnt(12)
	v_mfma_f32_16x16x32_bf16 v[4:7], v[164:167], v[160:163], v[4:7]
	v_mfma_f32_16x16x32_bf16 v[0:3], v[168:171], v[160:163], v[0:3]
	global_load_dwordx4 v[64:67], v[20:21], off offset:1536
	global_load_dwordx4 v[68:71], v[22:23], off offset:1536
	global_load_dwordx4 v[72:75], v[24:25], off offset:1536
	s_waitcnt vmcnt(18)
	s_waitcnt lgkmcnt(3)
	ds_bpermute_b32 v160, v45, v88
	ds_bpermute_b32 v161, v45, v89
	ds_bpermute_b32 v162, v45, v90
	ds_bpermute_b32 v163, v45, v91
	ds_bpermute_b32 v164, v45, v92
	ds_bpermute_b32 v165, v45, v93
	ds_bpermute_b32 v166, v45, v94
	ds_bpermute_b32 v167, v45, v95
	ds_bpermute_b32 v168, v45, v96
	ds_bpermute_b32 v169, v45, v97
	ds_bpermute_b32 v170, v45, v98
	ds_bpermute_b32 v171, v45, v99
	s_waitcnt lgkmcnt(12)
	v_mfma_f32_16x16x32_bf16 v[4:7], v[176:179], v[172:175], v[4:7]
	v_mfma_f32_16x16x32_bf16 v[0:3], v[180:183], v[172:175], v[0:3]
	global_load_dwordx4 v[76:79], v[20:21], off offset:1600
	global_load_dwordx4 v[80:83], v[22:23], off offset:1600
	global_load_dwordx4 v[84:87], v[24:25], off offset:1600
	s_waitcnt vmcnt(18)
	s_waitcnt lgkmcnt(3)
	ds_bpermute_b32 v172, v45, v100
	ds_bpermute_b32 v173, v45, v101
	ds_bpermute_b32 v174, v45, v102
	ds_bpermute_b32 v175, v45, v103
	ds_bpermute_b32 v176, v45, v104
	ds_bpermute_b32 v177, v45, v105
	ds_bpermute_b32 v178, v45, v106
	ds_bpermute_b32 v179, v45, v107
	ds_bpermute_b32 v180, v45, v108
	ds_bpermute_b32 v181, v45, v109
	ds_bpermute_b32 v182, v45, v110
	ds_bpermute_b32 v183, v45, v111
	s_waitcnt lgkmcnt(12)
	v_mfma_f32_16x16x32_bf16 v[4:7], v[164:167], v[160:163], v[4:7]
	v_mfma_f32_16x16x32_bf16 v[0:3], v[168:171], v[160:163], v[0:3]
	global_load_dwordx4 v[88:91], v[20:21], off offset:1664
	global_load_dwordx4 v[92:95], v[22:23], off offset:1664
	global_load_dwordx4 v[96:99], v[24:25], off offset:1664
	s_waitcnt vmcnt(18)
; DEVI f32x4 mfma16(bf16x8 a, bf16x8 b, f32x4 c) { return __builtin_amdgcn_mfma_f32_16x16x32_bf16(a, b, c, 0, 0, 0); }
; DEVI void mini_kloop(const bf16_t* __restrict__ arow, const bf16_t* __restrict__ b0, const bf16_t* __restrict__ b1, const int K, f32x4 (&acc)[2]) {
; #pragma unroll 8
;     for (int k0 = 0; k0 < K; k0 += 32) {
;         const bf16x8 af = *(const bf16x8*)(arow + k0), w0 = *(const bf16x8*)(b0 + k0), w1 = *(const bf16x8*)(b1 + k0);
;         acc[0] = mfma16(w0, af, acc[0]); acc[1] = mfma16(w1, af, acc[1]);
;     }
; }
; DEVI void mini_y_tile(const Params& p, const int t) {
;     ...
;     mini_kloop(MX + (size_t)tok * 1024 + 8 * g, WOT + (size_t)(colw + l15) * 1024 + 8 * g, WOT + (size_t)(colw + 16 + l15) * 1024 + 8 * g, 1024, acc);
	s_waitcnt lgkmcnt(3)
	ds_bpermute_b32 v160, v45, v112
	ds_bpermute_b32 v161, v45, v113
	ds_bpermute_b32 v162, v45, v114
	ds_bpermute_b32 v163, v45, v115
	ds_bpermute_b32 v164, v45, v116
	ds_bpermute_b32 v165, v45, v117
	ds_bpermute_b32 v166, v45, v118
	ds_bpermute_b32 v167, v45, v119
	ds_bpermute_b32 v168, v45, v120
	ds_bpermute_b32 v169, v45, v121
	ds_bpermute_b32 v170, v45, v122
	ds_bpermute_b32 v171, v45, v123
	s_waitcnt lgkmcnt(12)
	v_mfma_f32_16x16x32_bf16 v[4:7], v[176:179], v[172:175], v[4:7]
	v_mfma_f32_16x16x32_bf16 v[0:3], v[180:183], v[172:175], v[0:3]
	global_load_dwordx4 v[100:103], v[20:21], off offset:1728
	global_load_dwordx4 v[104:107], v[22:23], off offset:1728
	global_load_dwordx4 v[108:111], v[24:25], off offset:1728
	s_waitcnt vmcnt(18)
	s_waitcnt lgkmcnt(3)
	ds_bpermute_b32 v172, v45, v124
	ds_bpermute_b32 v173, v45, v125
	ds_bpermute_b32 v174, v45, v126
	ds_bpermute_b32 v175, v45, v127
	ds_bpermute_b32 v176, v45, v128
	ds_bpermute_b32 v177, v45, v129
	ds_bpermute_b32 v178, v45, v130
	ds_bpermute_b32 v179, v45, v131
	ds_bpermute_b32 v180, v45, v132
	ds_bpermute_b32 v181, v45, v133
	ds_bpermute_b32 v182, v45, v134
	ds_bpermute_b32 v183, v45, v135
	s_waitcnt lgkmcnt(12)
	v_mfma_f32_16x16x32_bf16 v[4:7], v[164:167], v[160:163], v[4:7]
	v_mfma_f32_16x16x32_bf16 v[0:3], v[168:171], v[160:163], v[0:3]
	global_load_dwordx4 v[112:115], v[20:21], off offset:1792
	global_load_dwordx4 v[116:119], v[22:23], off offset:1792
	global_load_dwordx4 v[120:123], v[24:25], off offset:1792
	s_waitcnt vmcnt(18)
	s_waitcnt lgkmcnt(3)
	ds_bpermute_b32 v160, v45, v136
	ds_bpermute_b32 v161, v45, v137
	ds_bpermute_b32 v162, v45, v138
	ds_bpermute_b32 v163, v45, v139
	ds_bpermute_b32 v164, v45, v140
	ds_bpermute_b32 v165, v45, v141
	ds_bpermute_b32 v166, v45, v142
	ds_bpermute_b32 v167, v45, v143
	ds_bpermute_b32 v168, v45, v144
	ds_bpermute_b32 v169, v45, v145
	ds_bpermute_b32 v170, v45, v146
	ds_bpermute_b32 v171, v45, v147
	s_waitcnt lgkmcnt(12)
	v_mfma_f32_16x16x32_bf16 v[4:7], v[176:179], v[172:175], v[4:7]
	v_mfma_f32_16x16x32_bf16 v[0:3], v[180:183], v[172:175], v[0:3]
	global_load_dwordx4 v[124:127], v[20:21], off offset:1856
	global_load_dwordx4 v[128:131], v[22:23], off offset:1856
	global_load_dwordx4 v[132:135], v[24:25], off offset:1856
	s_waitcnt vmcnt(18)
	s_waitcnt lgkmcnt(3)
	ds_bpermute_b32 v172, v45, v148
	ds_bpermute_b32 v173, v45, v149
	ds_bpermute_b32 v174, v45, v150
	ds_bpermute_b32 v175, v45, v151
	ds_bpermute_b32 v176, v45, v152
	ds_bpermute_b32 v177, v45, v153
	ds_bpermute_b32 v178, v45, v154
	ds_bpermute_b32 v179, v45, v155
	ds_bpermute_b32 v180, v45, v156
	ds_bpermute_b32 v181, v45, v157
	ds_bpermute_b32 v182, v45, v158
	ds_bpermute_b32 v183, v45, v159
	s_waitcnt lgkmcnt(12)
	v_mfma_f32_16x16x32_bf16 v[4:7], v[164:167], v[160:163], v[4:7]
	v_mfma_f32_16x16x32_bf16 v[0:3], v[168:171], v[160:163], v[0:3]
	global_load_dwordx4 v[136:139], v[20:21], off offset:1920
	global_load_dwordx4 v[140:143], v[22:23], off offset:1920
	global_load_dwordx4 v[144:147], v[24:25], off offset:1920
	s_waitcnt vmcnt(18)
	s_waitcnt lgkmcnt(3)
	ds_bpermute_b32 v160, v45, v64
	ds_bpermute_b32 v161, v45, v65
	ds_bpermute_b32 v162, v45, v66
	ds_bpermute_b32 v163, v45, v67
	ds_bpermute_b32 v164, v45, v68
	ds_bpermute_b32 v165, v45, v69
	ds_bpermute_b32 v166, v45, v70
	ds_bpermute_b32 v167, v45, v71
	ds_bpermute_b32 v168, v45, v72
	ds_bpermute_b32 v169, v45, v73
	ds_bpermute_b32 v170, v45, v74
	ds_bpermute_b32 v171, v45, v75
	s_waitcnt lgkmcnt(12)
	v_mfma_f32_16x16x32_bf16 v[4:7], v[176:179], v[172:175], v[4:7]
	v_mfma_f32_16x16x32_bf16 v[0:3], v[180:183], v[172:175], v[0:3]
	global_load_dwordx4 v[148:151], v[20:21], off offset:1984
	global_load_dwordx4 v[152:155], v[22:23], off offset:1984
	global_load_dwordx4 v[156:159], v[24:25], off offset:1984
	s_waitcnt vmcnt(18)
	s_waitcnt lgkmcnt(3)
	ds_bpermute_b32 v172, v45, v76
	ds_bpermute_b32 v173, v45, v77
	ds_bpermute_b32 v174, v45, v78
	ds_bpermute_b32 v175, v45, v79
	ds_bpermute_b32 v176, v45, v80
	ds_bpermute_b32 v177, v45, v81
	ds_bpermute_b32 v178, v45, v82
	ds_bpermute_b32 v179, v45, v83
	ds_bpermute_b32 v180, v45, v84
	ds_bpermute_b32 v181, v45, v85
	ds_bpermute_b32 v182, v45, v86
	ds_bpermute_b32 v183, v45, v87
	s_waitcnt lgkmcnt(12)
	v_mfma_f32_16x16x32_bf16 v[4:7], v[164:167], v[160:163], v[4:7]
	v_mfma_f32_16x16x32_bf16 v[0:3], v[168:171], v[160:163], v[0:3]
	s_waitcnt vmcnt(15)
	s_waitcnt lgkmcnt(3)
	ds_bpermute_b32 v160, v45, v88
	ds_bpermute_b32 v161, v45, v89
	ds_bpermute_b32 v162, v45, v90
	ds_bpermute_b32 v163, v45, v91
	ds_bpermute_b32 v164, v45, v92
	ds_bpermute_b32 v165, v45, v93
	ds_bpermute_b32 v166, v45, v94
	ds_bpermute_b32 v167, v45, v95
	ds_bpermute_b32 v168, v45, v96
	ds_bpermute_b32 v169, v45, v97
	ds_bpermute_b32 v170, v45, v98
	ds_bpermute_b32 v171, v45, v99
	s_waitcnt lgkmcnt(12)
	v_mfma_f32_16x16x32_bf16 v[4:7], v[176:179], v[172:175], v[4:7]
	v_mfma_f32_16x16x32_bf16 v[0:3], v[180:183], v[172:175], v[0:3]
	s_waitcnt vmcnt(12)
	s_waitcnt lgkmcnt(3)
; DEVI f32x4 mfma16(bf16x8 a, bf16x8 b, f32x4 c) { return __builtin_amdgcn_mfma_f32_16x16x32_bf16(a, b, c, 0, 0, 0); }
; DEVI void mini_kloop(const bf16_t* __restrict__ arow, const bf16_t* __restrict__ b0, const bf16_t* __restrict__ b1, const int K, f32x4 (&acc)[2]) {
; #pragma unroll 8
;     for (int k0 = 0; k0 < K; k0 += 32) {
;         const bf16x8 af = *(const bf16x8*)(arow + k0), w0 = *(const bf16x8*)(b0 + k0), w1 = *(const bf16x8*)(b1 + k0);
;         acc[0] = mfma16(w0, af, acc[0]); acc[1] = mfma16(w1, af, acc[1]);
;     }
; }
; DEVI void mini_y_tile(const Params& p, const int t) {
;     ...
;     const float* xr = p.x_s + (size_t)(tok - NTP) * 1024;
; #pragma unroll
;     for (int tt = 0; tt < 2; ++tt) {
;         const int col = colw + 16 * tt + 4 * g;
;         const f32x4 xv = *(const f32x4*)(xr + col);
;         *(f32x4*)(p.out + (size_t)tok * 1024 + col) = xv + acc[tt];
;     }
	ds_bpermute_b32 v172, v45, v100
	ds_bpermute_b32 v173, v45, v101
	ds_bpermute_b32 v174, v45, v102
	ds_bpermute_b32 v175, v45, v103
	ds_bpermute_b32 v176, v45, v104
	ds_bpermute_b32 v177, v45, v105
	ds_bpermute_b32 v178, v45, v106
	ds_bpermute_b32 v179, v45, v107
	ds_bpermute_b32 v180, v45, v108
	ds_bpermute_b32 v181, v45, v109
	ds_bpermute_b32 v182, v45, v110
	ds_bpermute_b32 v183, v45, v111
	s_waitcnt lgkmcnt(12)
	v_mfma_f32_16x16x32_bf16 v[4:7], v[164:167], v[160:163], v[4:7]
	v_mfma_f32_16x16x32_bf16 v[0:3], v[168:171], v[160:163], v[0:3]
	s_waitcnt vmcnt(9)
	s_waitcnt lgkmcnt(3)
	ds_bpermute_b32 v160, v45, v112
	ds_bpermute_b32 v161, v45, v113
	ds_bpermute_b32 v162, v45, v114
	ds_bpermute_b32 v163, v45, v115
	ds_bpermute_b32 v164, v45, v116
	ds_bpermute_b32 v165, v45, v117
	ds_bpermute_b32 v166, v45, v118
	ds_bpermute_b32 v167, v45, v119
	ds_bpermute_b32 v168, v45, v120
	ds_bpermute_b32 v169, v45, v121
	ds_bpermute_b32 v170, v45, v122
	ds_bpermute_b32 v171, v45, v123
	s_waitcnt lgkmcnt(12)
	v_mfma_f32_16x16x32_bf16 v[4:7], v[176:179], v[172:175], v[4:7]
	v_mfma_f32_16x16x32_bf16 v[0:3], v[180:183], v[172:175], v[0:3]
	s_waitcnt vmcnt(6)
	s_waitcnt lgkmcnt(3)
	ds_bpermute_b32 v172, v45, v124
	ds_bpermute_b32 v173, v45, v125
	ds_bpermute_b32 v174, v45, v126
	ds_bpermute_b32 v175, v45, v127
	ds_bpermute_b32 v176, v45, v128
	ds_bpermute_b32 v177, v45, v129
	ds_bpermute_b32 v178, v45, v130
	ds_bpermute_b32 v179, v45, v131
	ds_bpermute_b32 v180, v45, v132
	ds_bpermute_b32 v181, v45, v133
	ds_bpermute_b32 v182, v45, v134
	ds_bpermute_b32 v183, v45, v135
	s_waitcnt lgkmcnt(12)
	v_mfma_f32_16x16x32_bf16 v[4:7], v[164:167], v[160:163], v[4:7]
	v_mfma_f32_16x16x32_bf16 v[0:3], v[168:171], v[160:163], v[0:3]
	s_waitcnt vmcnt(3)
	s_waitcnt lgkmcnt(3)
	ds_bpermute_b32 v160, v45, v136
	ds_bpermute_b32 v161, v45, v137
	ds_bpermute_b32 v162, v45, v138
	ds_bpermute_b32 v163, v45, v139
	ds_bpermute_b32 v164, v45, v140
	ds_bpermute_b32 v165, v45, v141
	ds_bpermute_b32 v166, v45, v142
	ds_bpermute_b32 v167, v45, v143
	ds_bpermute_b32 v168, v45, v144
	ds_bpermute_b32 v169, v45, v145
	ds_bpermute_b32 v170, v45, v146
	ds_bpermute_b32 v171, v45, v147
	s_waitcnt lgkmcnt(12)
	v_mfma_f32_16x16x32_bf16 v[4:7], v[176:179], v[172:175], v[4:7]
	v_mfma_f32_16x16x32_bf16 v[0:3], v[180:183], v[172:175], v[0:3]
	s_waitcnt vmcnt(0)
	s_waitcnt lgkmcnt(3)
	ds_bpermute_b32 v172, v45, v148
	ds_bpermute_b32 v173, v45, v149
	ds_bpermute_b32 v174, v45, v150
	ds_bpermute_b32 v175, v45, v151
	ds_bpermute_b32 v176, v45, v152
	ds_bpermute_b32 v177, v45, v153
	ds_bpermute_b32 v178, v45, v154
	ds_bpermute_b32 v179, v45, v155
	ds_bpermute_b32 v180, v45, v156
	ds_bpermute_b32 v181, v45, v157
	ds_bpermute_b32 v182, v45, v158
	ds_bpermute_b32 v183, v45, v159
	s_waitcnt lgkmcnt(12)
	v_mfma_f32_16x16x32_bf16 v[4:7], v[164:167], v[160:163], v[4:7]
	v_mfma_f32_16x16x32_bf16 v[0:3], v[168:171], v[160:163], v[0:3]
	s_waitcnt lgkmcnt(0)
	v_mfma_f32_16x16x32_bf16 v[4:7], v[176:179], v[172:175], v[4:7]
	v_mfma_f32_16x16x32_bf16 v[0:3], v[180:183], v[172:175], v[0:3]
	s_lshl_b32 s3, s11, 2
	s_andn2_b32 s3, s3, 63
	s_add_i32 s3, s3, 0x8000
	v_or3_b32 v10, v17, s3, v16
	s_lshl_b32 s3, s11, 6
	s_and_b32 s3, s3, 0x3c0
	v_and_b32_e32 v8, 3, v19
	v_add_u32_e32 v12, s3, v18
	v_ashrrev_i32_e32 v11, 31, v10
	v_readlane_b32 s12, v234, 2
	v_lshl_or_b32 v12, v8, 2, v12
	v_lshlrev_b64 v[14:15], 12, v[10:11]
	v_readlane_b32 s14, v234, 4
	v_readlane_b32 s15, v234, 5
	v_ashrrev_i32_e32 v13, 31, v12
	v_lshlrev_b64 v[16:17], 2, v[12:13]
	v_lshl_add_u64 v[10:11], s[14:15], 0, v[14:15]
	v_lshl_add_u64 v[18:19], v[10:11], 0, v[16:17]
	v_add_co_u32_e32 v10, vcc, s10, v18
	v_readlane_b32 s13, v234, 3
	s_nop 0
	v_addc_co_u32_e32 v11, vcc, -1, v19, vcc
	global_load_dwordx4 v[10:13], v[10:11], off
	v_readlane_b32 s16, v234, 6
	v_readlane_b32 s17, v234, 7
	v_readlane_b32 s18, v234, 8
	v_readlane_b32 s19, v234, 9
	v_readlane_b32 s20, v234, 10
	v_readlane_b32 s21, v234, 11
	v_readlane_b32 s22, v234, 12
	v_readlane_b32 s23, v234, 13
	v_readlane_b32 s24, v234, 14
	v_readlane_b32 s25, v234, 15
	v_readlane_b32 s26, v234, 16
	v_readlane_b32 s27, v234, 17
	v_readlane_b32 s12, v234, 24
	v_readlane_b32 s26, v234, 38
	v_readlane_b32 s27, v234, 39
	s_add_i32 s11, s11, s97
	s_add_i32 s2, s2, s6
	v_lshl_add_u64 v[14:15], s[26:27], 0, v[14:15]
	v_lshl_add_u64 v[14:15], v[14:15], 0, v[16:17]
	v_lshl_add_u64 v[16:17], v[18:19], 0, s[4:5]
	s_add_i32 s7, s7, s8
	s_cmpk_gt_i32 s11, 0xff
	v_readlane_b32 s13, v234, 25
	v_readlane_b32 s14, v234, 26
	v_readlane_b32 s15, v234, 27
	v_readlane_b32 s16, v234, 28
	v_readlane_b32 s17, v234, 29
	v_readlane_b32 s18, v234, 30
	v_readlane_b32 s19, v234, 31
	v_readlane_b32 s20, v234, 32
	v_readlane_b32 s21, v234, 33
	v_readlane_b32 s22, v234, 34
	v_readlane_b32 s23, v234, 35
	v_readlane_b32 s24, v234, 36
	v_readlane_b32 s25, v234, 37
	s_waitcnt vmcnt(0)
	v_pk_add_f32 v[6:7], v[6:7], v[12:13]
	v_pk_add_f32 v[4:5], v[4:5], v[10:11]
	global_store_dwordx4 v[14:15], v[4:7], off
	global_load_dwordx4 v[4:7], v[16:17], off offset:64
	s_waitcnt vmcnt(0)
	v_pk_add_f32 v[2:3], v[2:3], v[6:7]
	v_pk_add_f32 v[0:1], v[0:1], v[4:5]
	global_store_dwordx4 v[14:15], v[0:3], off offset:64
	s_cbranch_scc0 .LBB0_1207
